# first K-iteration after an epilogue skips the two vmcnt waits whose loads the epilogue already retired (flag in s101); EpiQG q-path row-stat loads hoisted
# speedup vs baseline: 1.0063x; 1.0063x over previous
.LBB0_22:
	s_mov_b32 s101, 0
	v_readlane_b32 s0, v251, 3
	v_readlane_b32 s1, v251, 4
	s_ashr_i32 s1, s0, 31
	s_add_u32 s0, s48, s0
	s_addc_u32 s1, s49, s1
	v_mov_b32_e32 v172, v171
	s_nop 0
	global_load_sbyte v0, v97, s[0:1] offset:280
	v_readlane_b32 s0, v251, 5
	v_readlane_b32 s1, v251, 6
	s_load_dword s1, s[0:1], 0x0
	v_readlane_b32 s0, v251, 0
	s_mov_b32 s4, s0
	v_readfirstlane_b32 s0, v172
	s_waitcnt vmcnt(0)
	v_readfirstlane_b32 s3, v0
	v_writelane_b32 v251, s0, 13
	s_waitcnt lgkmcnt(0)
	v_writelane_b32 v251, s1, 14
	s_and_b32 s0, s1, 7
	v_writelane_b32 v251, s1, 15
	s_cmp_lg_u32 s0, 0
	s_mov_b32 s0, s4
	s_cbranch_scc1 .LBB0_24
	s_ashr_i32 s1, s4, 31
	s_lshr_b32 s1, s1, 29
	s_add_i32 s1, s4, s1
	v_readlane_b32 s0, v251, 15
	s_and_b32 s2, s1, -8
	s_ashr_i32 s0, s0, 3
	s_sub_i32 s2, s4, s2
	s_mul_i32 s0, s2, s0
	s_ashr_i32 s1, s1, 3
	s_add_i32 s0, s0, s1

.LBB0_714:
	v_lshl_or_b32 v144, s39, 8, v148
	v_ashrrev_i32_e32 v143, 31, v142
	v_readlane_b32 s0, v251, 24
	v_ashrrev_i32_e32 v145, 31, v144
	v_lshlrev_b64 v[150:151], 11, v[142:143]
	v_readlane_b32 s1, v251, 25
	v_lshlrev_b64 v[144:145], 1, v[144:145]
	s_nop 0
	v_lshl_add_u64 v[150:151], s[0:1], 0, v[150:151]
	v_lshl_add_u64 v[154:155], v[150:151], 0, v[144:145]
	v_lshl_add_u64 v[150:151], v[142:143], 4, s[10:11]
	global_load_dwordx4 v[150:153], v[150:151], off
	v_or_b32_e32 v194, 16, v142
	v_ashrrev_i32_e32 v195, 31, v194
	v_lshl_add_u64 v[158:159], v[194:195], 4, s[10:11]
	global_load_dwordx4 v[158:161], v[158:159], off
	v_or_b32_e32 v194, 32, v142
	v_ashrrev_i32_e32 v195, 31, v194
	v_lshl_add_u64 v[162:163], v[194:195], 4, s[10:11]
	global_load_dwordx4 v[162:165], v[162:163], off
	v_or_b32_e32 v194, 48, v142
	v_ashrrev_i32_e32 v195, 31, v194
	v_lshl_add_u64 v[174:175], v[194:195], 4, s[10:11]
	global_load_dwordx4 v[174:177], v[174:175], off
	v_add_u32_e32 v194, 128, v142
	v_ashrrev_i32_e32 v195, 31, v194
	v_lshl_add_u64 v[178:179], v[194:195], 4, s[10:11]
	global_load_dwordx4 v[178:181], v[178:179], off
	v_add_u32_e32 v194, 144, v142
	v_ashrrev_i32_e32 v195, 31, v194
	v_lshl_add_u64 v[182:183], v[194:195], 4, s[10:11]
	global_load_dwordx4 v[182:185], v[182:183], off
	v_add_u32_e32 v194, 160, v142
	v_ashrrev_i32_e32 v195, 31, v194
	v_lshl_add_u64 v[186:187], v[194:195], 4, s[10:11]
	global_load_dwordx4 v[186:189], v[186:187], off
	v_add_u32_e32 v194, 176, v142
	v_ashrrev_i32_e32 v195, 31, v194
	v_lshl_add_u64 v[190:191], v[194:195], 4, s[10:11]
	global_load_dwordx4 v[190:193], v[190:191], off
	s_waitcnt vmcnt(7)
	v_mov_b32_e32 v156, v151
	v_mov_b32_e32 v157, v152
	v_mov_b32_e32 v151, v153
	v_pk_add_f32 v[150:151], v[156:157], v[150:151]
	s_nop 0
	v_add_f32_e32 v143, v150, v151
	v_fmamk_f32 v143, v143, 0x3a800000, v207
	v_rsq_f32_e32 v150, v143
	s_nop 0
	v_pk_mul_f32 v[128:129], v[128:129], v[150:151] op_sel_hi:[1,0]
	v_pk_mul_f32 v[126:127], v[126:127], v[150:151] op_sel_hi:[1,0]
	v_pk_mul_f32 v[152:153], v[124:125], v[150:151] op_sel_hi:[1,0]
	v_pk_mul_f32 v[124:125], v[122:123], v[150:151] op_sel_hi:[1,0]
	v_cvt_pk_bf16_f32 v122, v126, v127
	v_cvt_pk_bf16_f32 v123, v128, v129
	v_pk_mul_f32 v[118:119], v[118:119], v[150:151] op_sel_hi:[1,0]
	v_cvt_pk_bf16_f32 v124, v124, v125
	v_cvt_pk_bf16_f32 v125, v152, v153
	global_store_dwordx4 v[154:155], v[122:125], off
	v_pk_mul_f32 v[120:121], v[120:121], v[150:151] op_sel_hi:[1,0]
	s_nop 0
	v_pk_mul_f32 v[122:123], v[116:117], v[150:151] op_sel_hi:[1,0]
	v_pk_mul_f32 v[116:117], v[114:115], v[150:151] op_sel_hi:[1,0]
	v_cvt_pk_bf16_f32 v114, v118, v119
	v_cvt_pk_bf16_f32 v115, v120, v121
	s_nop 0
	v_cvt_pk_bf16_f32 v116, v116, v117
	v_cvt_pk_bf16_f32 v117, v122, v123
	global_store_dwordx4 v[154:155], v[114:117], off offset:256
	s_nop 1
	v_or_b32_e32 v114, 16, v142
	v_ashrrev_i32_e32 v115, 31, v114
	v_lshlrev_b64 v[116:117], 11, v[114:115]
	v_lshl_add_u64 v[116:117], s[0:1], 0, v[116:117]
	v_lshl_add_u64 v[118:119], v[116:117], 0, v[144:145]
	s_waitcnt vmcnt(8)
	v_mov_b32_e32 v114, v158
	v_mov_b32_e32 v115, v159
	v_mov_b32_e32 v116, v160
	v_mov_b32_e32 v117, v161
	v_mov_b32_e32 v120, v115
	v_mov_b32_e32 v121, v116
	v_mov_b32_e32 v115, v117
	v_pk_add_f32 v[114:115], v[120:121], v[114:115]
	s_nop 0
	v_add_f32_e32 v114, v114, v115
	v_fmamk_f32 v114, v114, 0x3a800000, v207
	v_rsq_f32_e32 v114, v114
	s_nop 0
	v_pk_mul_f32 v[112:113], v[112:113], v[114:115] op_sel_hi:[1,0]
	v_pk_mul_f32 v[110:111], v[110:111], v[114:115] op_sel_hi:[1,0]
	v_pk_mul_f32 v[116:117], v[108:109], v[114:115] op_sel_hi:[1,0]
	v_pk_mul_f32 v[108:109], v[106:107], v[114:115] op_sel_hi:[1,0]
	v_cvt_pk_bf16_f32 v106, v110, v111
	v_cvt_pk_bf16_f32 v107, v112, v113
	v_pk_mul_f32 v[102:103], v[102:103], v[114:115] op_sel_hi:[1,0]
	v_cvt_pk_bf16_f32 v108, v108, v109
	v_cvt_pk_bf16_f32 v109, v116, v117
	global_store_dwordx4 v[118:119], v[106:109], off
	v_pk_mul_f32 v[104:105], v[104:105], v[114:115] op_sel_hi:[1,0]
	s_nop 0
	v_pk_mul_f32 v[106:107], v[100:101], v[114:115] op_sel_hi:[1,0]
	v_pk_mul_f32 v[100:101], v[98:99], v[114:115] op_sel_hi:[1,0]
	v_cvt_pk_bf16_f32 v98, v102, v103
	v_cvt_pk_bf16_f32 v99, v104, v105
	s_nop 0
	v_cvt_pk_bf16_f32 v100, v100, v101
	v_cvt_pk_bf16_f32 v101, v106, v107
	global_store_dwordx4 v[118:119], v[98:101], off offset:256
	s_nop 1
	v_or_b32_e32 v98, 32, v142
	v_ashrrev_i32_e32 v99, 31, v98
	v_lshlrev_b64 v[100:101], 11, v[98:99]
	v_lshl_add_u64 v[100:101], s[0:1], 0, v[100:101]
	v_lshl_add_u64 v[102:103], v[100:101], 0, v[144:145]
	s_waitcnt vmcnt(9)
	v_mov_b32_e32 v98, v162
	v_mov_b32_e32 v99, v163
	v_mov_b32_e32 v100, v164
	v_mov_b32_e32 v101, v165
	v_mov_b32_e32 v104, v99
	v_mov_b32_e32 v105, v100
	v_mov_b32_e32 v99, v101
	v_pk_add_f32 v[98:99], v[104:105], v[98:99]
	s_nop 0
	v_add_f32_e32 v98, v98, v99
	v_fmamk_f32 v98, v98, 0x3a800000, v207
	v_rsq_f32_e32 v98, v98
	s_nop 0
	v_pk_mul_f32 v[94:95], v[94:95], v[98:99] op_sel_hi:[1,0]
	v_pk_mul_f32 v[92:93], v[92:93], v[98:99] op_sel_hi:[1,0]
	v_pk_mul_f32 v[100:101], v[90:91], v[98:99] op_sel_hi:[1,0]
	v_pk_mul_f32 v[90:91], v[88:89], v[98:99] op_sel_hi:[1,0]
	v_cvt_pk_bf16_f32 v88, v92, v93
	v_cvt_pk_bf16_f32 v89, v94, v95
	v_pk_mul_f32 v[84:85], v[84:85], v[98:99] op_sel_hi:[1,0]
	v_cvt_pk_bf16_f32 v90, v90, v91
	v_cvt_pk_bf16_f32 v91, v100, v101
	global_store_dwordx4 v[102:103], v[88:91], off
	v_pk_mul_f32 v[86:87], v[86:87], v[98:99] op_sel_hi:[1,0]
	s_nop 0
	v_pk_mul_f32 v[88:89], v[82:83], v[98:99] op_sel_hi:[1,0]
	v_pk_mul_f32 v[82:83], v[80:81], v[98:99] op_sel_hi:[1,0]
	v_cvt_pk_bf16_f32 v80, v84, v85
	v_cvt_pk_bf16_f32 v81, v86, v87
	s_nop 0
	v_cvt_pk_bf16_f32 v82, v82, v83
	v_cvt_pk_bf16_f32 v83, v88, v89
	global_store_dwordx4 v[102:103], v[80:83], off offset:256
	s_nop 1
	v_or_b32_e32 v80, 48, v142
	v_ashrrev_i32_e32 v81, 31, v80
	v_lshlrev_b64 v[82:83], 11, v[80:81]
	v_lshl_add_u64 v[82:83], s[0:1], 0, v[82:83]
	v_lshl_add_u64 v[84:85], v[82:83], 0, v[144:145]
	s_waitcnt vmcnt(10)
	v_mov_b32_e32 v80, v174
	v_mov_b32_e32 v81, v175
	v_mov_b32_e32 v82, v176
	v_mov_b32_e32 v83, v177
	v_mov_b32_e32 v86, v81
	v_mov_b32_e32 v87, v82
	v_mov_b32_e32 v81, v83
	v_pk_add_f32 v[80:81], v[86:87], v[80:81]
	s_nop 0
	v_add_f32_e32 v80, v80, v81
	v_fmamk_f32 v80, v80, 0x3a800000, v207
	v_rsq_f32_e32 v80, v80
	s_nop 0
	v_pk_mul_f32 v[78:79], v[78:79], v[80:81] op_sel_hi:[1,0]
	v_pk_mul_f32 v[76:77], v[76:77], v[80:81] op_sel_hi:[1,0]
	v_pk_mul_f32 v[82:83], v[74:75], v[80:81] op_sel_hi:[1,0]
	v_pk_mul_f32 v[74:75], v[72:73], v[80:81] op_sel_hi:[1,0]
	v_cvt_pk_bf16_f32 v72, v76, v77
	v_cvt_pk_bf16_f32 v73, v78, v79
	v_pk_mul_f32 v[68:69], v[68:69], v[80:81] op_sel_hi:[1,0]
	v_cvt_pk_bf16_f32 v74, v74, v75
	v_cvt_pk_bf16_f32 v75, v82, v83
	global_store_dwordx4 v[84:85], v[72:75], off
	v_pk_mul_f32 v[70:71], v[70:71], v[80:81] op_sel_hi:[1,0]
	s_nop 0
	v_pk_mul_f32 v[72:73], v[66:67], v[80:81] op_sel_hi:[1,0]
	v_pk_mul_f32 v[66:67], v[64:65], v[80:81] op_sel_hi:[1,0]
	v_cvt_pk_bf16_f32 v64, v68, v69
	v_cvt_pk_bf16_f32 v65, v70, v71
	s_nop 0
	v_cvt_pk_bf16_f32 v66, v66, v67
	v_cvt_pk_bf16_f32 v67, v72, v73
	global_store_dwordx4 v[84:85], v[64:67], off offset:256
	s_nop 1
	v_add_u32_e32 v64, 0x80, v142
	v_ashrrev_i32_e32 v65, 31, v64
	v_lshlrev_b64 v[66:67], 11, v[64:65]
	v_lshl_add_u64 v[66:67], s[0:1], 0, v[66:67]
	v_lshl_add_u64 v[68:69], v[66:67], 0, v[144:145]
	s_waitcnt vmcnt(11)
	v_mov_b32_e32 v64, v178
	v_mov_b32_e32 v65, v179
	v_mov_b32_e32 v66, v180
	v_mov_b32_e32 v67, v181
	v_mov_b32_e32 v70, v65
	v_mov_b32_e32 v71, v66
	v_mov_b32_e32 v65, v67
	v_pk_add_f32 v[64:65], v[70:71], v[64:65]
	s_nop 0
	v_add_f32_e32 v64, v64, v65
	v_fmamk_f32 v64, v64, 0x3a800000, v207
	v_rsq_f32_e32 v64, v64
	s_nop 0
	v_pk_mul_f32 v[62:63], v[62:63], v[64:65] op_sel_hi:[1,0]
	v_pk_mul_f32 v[60:61], v[60:61], v[64:65] op_sel_hi:[1,0]
	v_pk_mul_f32 v[66:67], v[58:59], v[64:65] op_sel_hi:[1,0]
	v_pk_mul_f32 v[58:59], v[56:57], v[64:65] op_sel_hi:[1,0]
	v_cvt_pk_bf16_f32 v56, v60, v61
	v_cvt_pk_bf16_f32 v57, v62, v63
	v_pk_mul_f32 v[52:53], v[52:53], v[64:65] op_sel_hi:[1,0]
	v_cvt_pk_bf16_f32 v58, v58, v59
	v_cvt_pk_bf16_f32 v59, v66, v67
	global_store_dwordx4 v[68:69], v[56:59], off
	v_pk_mul_f32 v[54:55], v[54:55], v[64:65] op_sel_hi:[1,0]
	s_nop 0
	v_pk_mul_f32 v[56:57], v[50:51], v[64:65] op_sel_hi:[1,0]
	v_pk_mul_f32 v[50:51], v[48:49], v[64:65] op_sel_hi:[1,0]
	v_cvt_pk_bf16_f32 v48, v52, v53
	v_cvt_pk_bf16_f32 v49, v54, v55
	s_nop 0
	v_cvt_pk_bf16_f32 v50, v50, v51
	v_cvt_pk_bf16_f32 v51, v56, v57
	global_store_dwordx4 v[68:69], v[48:51], off offset:256
	s_nop 1
	v_add_u32_e32 v48, 0x90, v142
	v_ashrrev_i32_e32 v49, 31, v48
	v_lshlrev_b64 v[50:51], 11, v[48:49]
	v_lshl_add_u64 v[50:51], s[0:1], 0, v[50:51]
	v_lshl_add_u64 v[52:53], v[50:51], 0, v[144:145]
	s_waitcnt vmcnt(12)
	v_mov_b32_e32 v48, v182
	v_mov_b32_e32 v49, v183
	v_mov_b32_e32 v50, v184
	v_mov_b32_e32 v51, v185
	v_mov_b32_e32 v54, v49
	v_mov_b32_e32 v55, v50
	v_mov_b32_e32 v49, v51
	v_pk_add_f32 v[48:49], v[54:55], v[48:49]
	s_nop 0
	v_add_f32_e32 v48, v48, v49
	v_fmamk_f32 v48, v48, 0x3a800000, v207
	v_rsq_f32_e32 v48, v48
	s_nop 0
	v_pk_mul_f32 v[46:47], v[46:47], v[48:49] op_sel_hi:[1,0]
	v_pk_mul_f32 v[44:45], v[44:45], v[48:49] op_sel_hi:[1,0]
	v_pk_mul_f32 v[50:51], v[42:43], v[48:49] op_sel_hi:[1,0]
	v_pk_mul_f32 v[42:43], v[40:41], v[48:49] op_sel_hi:[1,0]
	v_cvt_pk_bf16_f32 v40, v44, v45
	v_cvt_pk_bf16_f32 v41, v46, v47
	v_pk_mul_f32 v[36:37], v[36:37], v[48:49] op_sel_hi:[1,0]
	v_cvt_pk_bf16_f32 v42, v42, v43
	v_cvt_pk_bf16_f32 v43, v50, v51
	global_store_dwordx4 v[52:53], v[40:43], off
	v_pk_mul_f32 v[38:39], v[38:39], v[48:49] op_sel_hi:[1,0]
	s_nop 0
	v_pk_mul_f32 v[40:41], v[34:35], v[48:49] op_sel_hi:[1,0]
	v_pk_mul_f32 v[34:35], v[32:33], v[48:49] op_sel_hi:[1,0]
	v_cvt_pk_bf16_f32 v32, v36, v37
	v_cvt_pk_bf16_f32 v33, v38, v39
	s_nop 0
	v_cvt_pk_bf16_f32 v34, v34, v35
	v_cvt_pk_bf16_f32 v35, v40, v41
	global_store_dwordx4 v[52:53], v[32:35], off offset:256
	s_nop 1
	v_add_u32_e32 v32, 0xa0, v142
	v_ashrrev_i32_e32 v33, 31, v32
	v_lshlrev_b64 v[34:35], 11, v[32:33]
	v_lshl_add_u64 v[34:35], s[0:1], 0, v[34:35]
	v_lshl_add_u64 v[36:37], v[34:35], 0, v[144:145]
	s_waitcnt vmcnt(13)
	v_mov_b32_e32 v32, v186
	v_mov_b32_e32 v33, v187
	v_mov_b32_e32 v34, v188
	v_mov_b32_e32 v35, v189
	v_mov_b32_e32 v38, v33
	v_mov_b32_e32 v39, v34
	v_mov_b32_e32 v33, v35
	v_pk_add_f32 v[32:33], v[38:39], v[32:33]
	s_nop 0
	v_add_f32_e32 v32, v32, v33
	v_fmamk_f32 v32, v32, 0x3a800000, v207
	v_rsq_f32_e32 v32, v32
	s_nop 0
	v_pk_mul_f32 v[30:31], v[30:31], v[32:33] op_sel_hi:[1,0]
	v_pk_mul_f32 v[28:29], v[28:29], v[32:33] op_sel_hi:[1,0]
	v_pk_mul_f32 v[34:35], v[26:27], v[32:33] op_sel_hi:[1,0]
	v_pk_mul_f32 v[26:27], v[24:25], v[32:33] op_sel_hi:[1,0]
	v_cvt_pk_bf16_f32 v24, v28, v29
	v_cvt_pk_bf16_f32 v25, v30, v31
	v_pk_mul_f32 v[20:21], v[20:21], v[32:33] op_sel_hi:[1,0]
	v_cvt_pk_bf16_f32 v26, v26, v27
	v_cvt_pk_bf16_f32 v27, v34, v35
	global_store_dwordx4 v[36:37], v[24:27], off
	v_pk_mul_f32 v[22:23], v[22:23], v[32:33] op_sel_hi:[1,0]
	s_nop 0
	v_pk_mul_f32 v[24:25], v[18:19], v[32:33] op_sel_hi:[1,0]
	v_pk_mul_f32 v[18:19], v[16:17], v[32:33] op_sel_hi:[1,0]
	v_cvt_pk_bf16_f32 v16, v20, v21
	v_cvt_pk_bf16_f32 v17, v22, v23
	s_nop 0
	v_cvt_pk_bf16_f32 v18, v18, v19
	v_cvt_pk_bf16_f32 v19, v24, v25
	global_store_dwordx4 v[36:37], v[16:19], off offset:256
	s_nop 1
	v_add_u32_e32 v16, 0xb0, v142
	v_ashrrev_i32_e32 v17, 31, v16
	v_lshlrev_b64 v[18:19], 11, v[16:17]
	v_lshl_add_u64 v[18:19], s[0:1], 0, v[18:19]
	v_lshl_add_u64 v[20:21], v[18:19], 0, v[144:145]
	s_waitcnt vmcnt(14)
	v_mov_b32_e32 v16, v190
	v_mov_b32_e32 v17, v191
	v_mov_b32_e32 v18, v192
	v_mov_b32_e32 v19, v193
	v_mov_b32_e32 v22, v17
	v_mov_b32_e32 v23, v18
	v_mov_b32_e32 v17, v19
	v_pk_add_f32 v[16:17], v[22:23], v[16:17]
	s_nop 0
	v_add_f32_e32 v16, v16, v17
	v_fmamk_f32 v16, v16, 0x3a800000, v207
	v_rsq_f32_e32 v16, v16
	s_nop 0
	v_pk_mul_f32 v[14:15], v[14:15], v[16:17] op_sel_hi:[1,0]
	v_pk_mul_f32 v[12:13], v[12:13], v[16:17] op_sel_hi:[1,0]
	v_pk_mul_f32 v[18:19], v[10:11], v[16:17] op_sel_hi:[1,0]
	v_pk_mul_f32 v[10:11], v[8:9], v[16:17] op_sel_hi:[1,0]
	v_cvt_pk_bf16_f32 v8, v12, v13
	v_cvt_pk_bf16_f32 v9, v14, v15
	v_pk_mul_f32 v[6:7], v[6:7], v[16:17] op_sel_hi:[1,0]
	v_cvt_pk_bf16_f32 v10, v10, v11
	v_cvt_pk_bf16_f32 v11, v18, v19
	global_store_dwordx4 v[20:21], v[8:11], off
	v_pk_mul_f32 v[4:5], v[4:5], v[16:17] op_sel_hi:[1,0]
	s_nop 0
	v_pk_mul_f32 v[8:9], v[2:3], v[16:17] op_sel_hi:[1,0]
	v_pk_mul_f32 v[2:3], v[0:1], v[16:17] op_sel_hi:[1,0]
	v_cvt_pk_bf16_f32 v0, v4, v5
	v_cvt_pk_bf16_f32 v1, v6, v7
	s_nop 0
	v_cvt_pk_bf16_f32 v2, v2, v3
	v_cvt_pk_bf16_f32 v3, v8, v9
	global_store_dwordx4 v[20:21], v[0:3], off offset:256
	s_andn2_b64 vcc, exec, s[6:7]
	s_mov_b64 s[0:1], -1
	s_cbranch_vccnz .LBB0_706
	s_branch .LBB0_720

.LBB0_944:
	s_add_u32 s66, s2, 1
	s_addc_u32 s67, s3, 0
	s_add_u32 s10, s2, 2
	s_addc_u32 s11, s3, 0
	s_lshl_b64 s[12:13], s[10:11], s54
	s_add_u32 s3, s0, s12
	s_addc_u32 s12, s1, s13
	s_cmp_eq_u32 s58, s2
	s_cselect_b32 s13, s31, s12
	s_cselect_b32 s12, s30, s3
	s_cselect_b32 s36, s48, s63
	s_cselect_b32 s37, s49, s64
	s_add_u32 s2, s12, s50
	s_addc_u32 s3, s13, 0
	s_add_i32 s65, 0, 0x10000
	s_add_i32 s68, 0, 0x14000
	v_add_u32_e32 v148, s65, v190
	v_add_u32_e32 v164, s68, v190
	ds_read_b128 v[136:139], v148
	ds_read_b128 v[140:143], v148 offset:1024
	ds_read_b128 v[144:147], v148 offset:2048
	ds_read_b128 v[148:151], v148 offset:3072
	ds_read_b128 v[152:155], v164
	ds_read_b128 v[156:159], v164 offset:1024
	ds_read_b128 v[160:163], v164 offset:2048
	ds_read_b128 v[164:167], v164 offset:3072
	s_lshl_b64 s[66:67], s[66:67], s54
	s_add_u32 s66, s61, s66
	s_addc_u32 s67, s62, s67
	v_lshl_add_u64 v[212:213], s[66:67], 0, v[130:131]
	s_add_i32 m0, s43, 0xc000
	ds_read_b128 v[174:177], v193
	ds_read_b128 v[178:181], v193 offset:1024
	ds_read_b128 v[182:185], v193 offset:2048
	ds_read_b128 v[186:189], v193 offset:3072
	ds_read_b128 v[194:197], v193 offset:4096
	ds_read_b128 v[198:201], v193 offset:5120
	ds_read_b128 v[202:205], v193 offset:6144
	ds_read_b128 v[222:225], v193 offset:7168
	global_load_lds_dwordx4 v[212:213], off
	v_lshl_add_u64 v[212:213], s[66:67], 0, v[132:133]
	s_add_i32 m0, s43, 0xe000
	s_nop 0
	global_load_lds_dwordx4 v[212:213], off
	s_cmp_eq_u32 s101, 1
	s_cbranch_scc1 .Lfw_1
	s_waitcnt vmcnt(8)
.Lfw_1:
	s_waitcnt lgkmcnt(0)
	s_barrier
	s_setprio 1
	s_waitcnt lgkmcnt(0)
	v_mfma_f32_16x16x32_bf16 v[126:129], v[136:139], v[174:177], v[126:129]
	v_mfma_f32_16x16x32_bf16 v[122:125], v[144:147], v[174:177], v[122:125]
	v_mfma_f32_16x16x32_bf16 v[110:113], v[136:139], v[182:185], v[110:113]
	v_mfma_f32_16x16x32_bf16 v[106:109], v[144:147], v[182:185], v[106:109]
	v_mfma_f32_16x16x32_bf16 v[92:95], v[136:139], v[194:197], v[92:95]
	v_mfma_f32_16x16x32_bf16 v[88:91], v[144:147], v[194:197], v[88:91]
	v_mfma_f32_16x16x32_bf16 v[76:79], v[136:139], v[202:205], v[76:79]
	v_mfma_f32_16x16x32_bf16 v[72:75], v[144:147], v[202:205], v[72:75]
	v_mfma_f32_16x16x32_bf16 v[126:129], v[140:143], v[178:181], v[126:129]
	v_mfma_f32_16x16x32_bf16 v[122:125], v[148:151], v[178:181], v[122:125]
	v_mfma_f32_16x16x32_bf16 v[110:113], v[140:143], v[186:189], v[110:113]
	v_mfma_f32_16x16x32_bf16 v[106:109], v[148:151], v[186:189], v[106:109]
	v_mfma_f32_16x16x32_bf16 v[92:95], v[140:143], v[198:201], v[92:95]
	v_mfma_f32_16x16x32_bf16 v[88:91], v[148:151], v[198:201], v[88:91]
	v_mfma_f32_16x16x32_bf16 v[76:79], v[140:143], v[222:225], v[76:79]
	v_mfma_f32_16x16x32_bf16 v[72:75], v[148:151], v[222:225], v[72:75]
	s_setprio 0
	s_setprio 1
	v_mfma_f32_16x16x32_bf16 v[118:121], v[152:155], v[174:177], v[118:121]
	v_mfma_f32_16x16x32_bf16 v[114:117], v[160:163], v[174:177], v[114:117]
	v_mfma_f32_16x16x32_bf16 v[102:105], v[152:155], v[182:185], v[102:105]
	v_mfma_f32_16x16x32_bf16 v[98:101], v[160:163], v[182:185], v[98:101]
	v_mfma_f32_16x16x32_bf16 v[84:87], v[152:155], v[194:197], v[84:87]
	v_mfma_f32_16x16x32_bf16 v[80:83], v[160:163], v[194:197], v[80:83]
	v_mfma_f32_16x16x32_bf16 v[68:71], v[152:155], v[202:205], v[68:71]
	v_mfma_f32_16x16x32_bf16 v[64:67], v[160:163], v[202:205], v[64:67]
	v_mfma_f32_16x16x32_bf16 v[118:121], v[156:159], v[178:181], v[118:121]
	v_mfma_f32_16x16x32_bf16 v[114:117], v[164:167], v[178:181], v[114:117]
	v_mfma_f32_16x16x32_bf16 v[102:105], v[156:159], v[186:189], v[102:105]
	v_mfma_f32_16x16x32_bf16 v[98:101], v[164:167], v[186:189], v[98:101]
	v_mfma_f32_16x16x32_bf16 v[84:87], v[156:159], v[198:201], v[84:87]
	v_mfma_f32_16x16x32_bf16 v[80:83], v[164:167], v[198:201], v[80:83]
	v_mfma_f32_16x16x32_bf16 v[68:71], v[156:159], v[222:225], v[68:71]
	v_mfma_f32_16x16x32_bf16 v[64:67], v[164:167], v[222:225], v[64:67]
	s_setprio 0
	s_barrier
	s_add_i32 s65, s65, s42
	v_lshl_add_u64 v[212:213], s[36:37], 0, v[96:97]
	s_mov_b32 m0, s65
	ds_read_b128 v[174:177], v193 offset:16384
	ds_read_b128 v[178:181], v193 offset:17408
	ds_read_b128 v[182:185], v193 offset:18432
	ds_read_b128 v[186:189], v193 offset:19456
	ds_read_b128 v[194:197], v193 offset:20480
	ds_read_b128 v[198:201], v193 offset:21504
	ds_read_b128 v[202:205], v193 offset:22528
	ds_read_b128 v[222:225], v193 offset:23552
	global_load_lds_dwordx4 v[212:213], off
	s_add_i32 m0, s65, 0x2000
	v_lshl_add_u64 v[214:215], s[36:37], 0, v[134:135]
	s_add_u32 s36, s36, s38
	s_addc_u32 s37, s37, 0
	s_add_i32 s65, s68, s42
	global_load_lds_dwordx4 v[214:215], off
	v_lshl_add_u64 v[220:221], s[36:37], 0, v[96:97]
	s_mov_b32 m0, s65
	v_lshl_add_u64 v[226:227], s[36:37], 0, v[134:135]
	global_load_lds_dwordx4 v[220:221], off
	s_add_i32 m0, s65, 0x2000
	v_lshl_add_u64 v[228:229], s[12:13], 0, v[130:131]
	global_load_lds_dwordx4 v[226:227], off
	s_mov_b32 m0, s43
	s_nop 0
	global_load_lds_dwordx4 v[228:229], off
	v_lshl_add_u64 v[228:229], s[12:13], 0, v[132:133]
	s_mov_b32 m0, s44
	s_nop 0
	global_load_lds_dwordx4 v[228:229], off
	s_cmp_eq_u32 s101, 1
	s_cbranch_scc1 .Lfw_2
	s_waitcnt vmcnt(8)
.Lfw_2:
	s_waitcnt lgkmcnt(0)
	s_barrier
	s_setprio 1
	s_waitcnt lgkmcnt(0)
	v_mfma_f32_16x16x32_bf16 v[60:63], v[136:139], v[174:177], v[60:63]
	v_mfma_f32_16x16x32_bf16 v[56:59], v[144:147], v[174:177], v[56:59]
	v_mfma_f32_16x16x32_bf16 v[44:47], v[136:139], v[182:185], v[44:47]
	v_mfma_f32_16x16x32_bf16 v[40:43], v[144:147], v[182:185], v[40:43]
	v_mfma_f32_16x16x32_bf16 v[28:31], v[136:139], v[194:197], v[28:31]
	v_mfma_f32_16x16x32_bf16 v[24:27], v[144:147], v[194:197], v[24:27]
	v_mfma_f32_16x16x32_bf16 v[12:15], v[136:139], v[202:205], v[12:15]
	v_mfma_f32_16x16x32_bf16 v[8:11], v[144:147], v[202:205], v[8:11]
	v_mfma_f32_16x16x32_bf16 v[60:63], v[140:143], v[178:181], v[60:63]
	v_mfma_f32_16x16x32_bf16 v[56:59], v[148:151], v[178:181], v[56:59]
	v_mfma_f32_16x16x32_bf16 v[44:47], v[140:143], v[186:189], v[44:47]
	v_mfma_f32_16x16x32_bf16 v[40:43], v[148:151], v[186:189], v[40:43]
	v_mfma_f32_16x16x32_bf16 v[28:31], v[140:143], v[198:201], v[28:31]
	v_mfma_f32_16x16x32_bf16 v[24:27], v[148:151], v[198:201], v[24:27]
	v_mfma_f32_16x16x32_bf16 v[12:15], v[140:143], v[222:225], v[12:15]
	v_mfma_f32_16x16x32_bf16 v[8:11], v[148:151], v[222:225], v[8:11]
	s_setprio 0
	s_setprio 1
	v_mfma_f32_16x16x32_bf16 v[52:55], v[152:155], v[174:177], v[52:55]
	v_mfma_f32_16x16x32_bf16 v[48:51], v[160:163], v[174:177], v[48:51]
	v_mfma_f32_16x16x32_bf16 v[36:39], v[152:155], v[182:185], v[36:39]
	v_mfma_f32_16x16x32_bf16 v[32:35], v[160:163], v[182:185], v[32:35]
	v_mfma_f32_16x16x32_bf16 v[20:23], v[152:155], v[194:197], v[20:23]
	v_mfma_f32_16x16x32_bf16 v[16:19], v[160:163], v[194:197], v[16:19]
	v_mfma_f32_16x16x32_bf16 v[4:7], v[152:155], v[202:205], v[4:7]
	v_mfma_f32_16x16x32_bf16 v[0:3], v[160:163], v[202:205], v[0:3]
	v_mfma_f32_16x16x32_bf16 v[52:55], v[156:159], v[178:181], v[52:55]
	v_mfma_f32_16x16x32_bf16 v[48:51], v[164:167], v[178:181], v[48:51]
	v_mfma_f32_16x16x32_bf16 v[36:39], v[156:159], v[186:189], v[36:39]
	v_mfma_f32_16x16x32_bf16 v[32:35], v[164:167], v[186:189], v[32:35]
	v_mfma_f32_16x16x32_bf16 v[20:23], v[156:159], v[198:201], v[20:23]
	v_mfma_f32_16x16x32_bf16 v[16:19], v[164:167], v[198:201], v[16:19]
	v_mfma_f32_16x16x32_bf16 v[4:7], v[156:159], v[222:225], v[4:7]
	v_mfma_f32_16x16x32_bf16 v[0:3], v[164:167], v[222:225], v[0:3]
	s_setprio 0
	s_barrier
	s_add_i32 s36, 0, 0x18000
	s_add_i32 s37, 0, 0x1c000
	v_add_u32_e32 v148, s36, v190
	v_add_u32_e32 v164, s37, v190
	ds_read_b128 v[136:139], v148
	ds_read_b128 v[140:143], v148 offset:1024
	ds_read_b128 v[144:147], v148 offset:2048
	ds_read_b128 v[148:151], v148 offset:3072
	ds_read_b128 v[152:155], v164
	ds_read_b128 v[156:159], v164 offset:1024
	ds_read_b128 v[160:163], v164 offset:2048
	ds_read_b128 v[164:167], v164 offset:3072
	s_add_u32 s12, s12, s41
	s_addc_u32 s13, s13, s40
	s_mov_b32 m0, s45
	v_lshl_add_u64 v[228:229], s[12:13], 0, v[130:131]
	ds_read_b128 v[174:177], v193 offset:32768
	ds_read_b128 v[178:181], v193 offset:33792
	ds_read_b128 v[182:185], v193 offset:34816
	ds_read_b128 v[186:189], v193 offset:35840
	ds_read_b128 v[194:197], v193 offset:36864
	ds_read_b128 v[198:201], v193 offset:37888
	ds_read_b128 v[202:205], v193 offset:38912
	ds_read_b128 v[222:225], v193 offset:39936
	global_load_lds_dwordx4 v[228:229], off
	v_lshl_add_u64 v[228:229], s[12:13], 0, v[132:133]
	s_mov_b32 m0, s46
	s_nop 0
	global_load_lds_dwordx4 v[228:229], off
	s_waitcnt vmcnt(8)
	s_waitcnt lgkmcnt(0)
	s_barrier
	s_setprio 1
	s_waitcnt lgkmcnt(0)
	v_mfma_f32_16x16x32_bf16 v[126:129], v[136:139], v[174:177], v[126:129]
	v_mfma_f32_16x16x32_bf16 v[122:125], v[144:147], v[174:177], v[122:125]
	v_mfma_f32_16x16x32_bf16 v[110:113], v[136:139], v[182:185], v[110:113]
	v_mfma_f32_16x16x32_bf16 v[106:109], v[144:147], v[182:185], v[106:109]
	v_mfma_f32_16x16x32_bf16 v[92:95], v[136:139], v[194:197], v[92:95]
	v_mfma_f32_16x16x32_bf16 v[88:91], v[144:147], v[194:197], v[88:91]
	v_mfma_f32_16x16x32_bf16 v[76:79], v[136:139], v[202:205], v[76:79]
	v_mfma_f32_16x16x32_bf16 v[72:75], v[144:147], v[202:205], v[72:75]
	v_mfma_f32_16x16x32_bf16 v[126:129], v[140:143], v[178:181], v[126:129]
	v_mfma_f32_16x16x32_bf16 v[122:125], v[148:151], v[178:181], v[122:125]
	v_mfma_f32_16x16x32_bf16 v[110:113], v[140:143], v[186:189], v[110:113]
	v_mfma_f32_16x16x32_bf16 v[106:109], v[148:151], v[186:189], v[106:109]
	v_mfma_f32_16x16x32_bf16 v[92:95], v[140:143], v[198:201], v[92:95]
	v_mfma_f32_16x16x32_bf16 v[88:91], v[148:151], v[198:201], v[88:91]
	v_mfma_f32_16x16x32_bf16 v[76:79], v[140:143], v[222:225], v[76:79]
	v_mfma_f32_16x16x32_bf16 v[72:75], v[148:151], v[222:225], v[72:75]
	s_setprio 0
	s_setprio 1
	v_mfma_f32_16x16x32_bf16 v[118:121], v[152:155], v[174:177], v[118:121]
	v_mfma_f32_16x16x32_bf16 v[114:117], v[160:163], v[174:177], v[114:117]
	v_mfma_f32_16x16x32_bf16 v[102:105], v[152:155], v[182:185], v[102:105]
	v_mfma_f32_16x16x32_bf16 v[98:101], v[160:163], v[182:185], v[98:101]
	v_mfma_f32_16x16x32_bf16 v[84:87], v[152:155], v[194:197], v[84:87]
	v_mfma_f32_16x16x32_bf16 v[80:83], v[160:163], v[194:197], v[80:83]
	v_mfma_f32_16x16x32_bf16 v[68:71], v[152:155], v[202:205], v[68:71]
	v_mfma_f32_16x16x32_bf16 v[64:67], v[160:163], v[202:205], v[64:67]
	v_mfma_f32_16x16x32_bf16 v[118:121], v[156:159], v[178:181], v[118:121]
	v_mfma_f32_16x16x32_bf16 v[114:117], v[164:167], v[178:181], v[114:117]
	v_mfma_f32_16x16x32_bf16 v[102:105], v[156:159], v[186:189], v[102:105]
	v_mfma_f32_16x16x32_bf16 v[98:101], v[164:167], v[186:189], v[98:101]
	v_mfma_f32_16x16x32_bf16 v[84:87], v[156:159], v[198:201], v[84:87]
	v_mfma_f32_16x16x32_bf16 v[80:83], v[164:167], v[198:201], v[80:83]
	v_mfma_f32_16x16x32_bf16 v[68:71], v[156:159], v[222:225], v[68:71]
	v_mfma_f32_16x16x32_bf16 v[64:67], v[164:167], v[222:225], v[64:67]
	s_setprio 0
	s_barrier
	s_add_i32 s12, s36, s42
	v_lshl_add_u64 v[212:213], v[212:213], 0, s[90:91]
	s_mov_b32 m0, s12
	ds_read_b128 v[174:177], v193 offset:49152
	ds_read_b128 v[178:181], v193 offset:50176
	ds_read_b128 v[182:185], v193 offset:51200
	ds_read_b128 v[186:189], v193 offset:52224
	ds_read_b128 v[194:197], v193 offset:53248
	ds_read_b128 v[198:201], v193 offset:54272
	ds_read_b128 v[202:205], v193 offset:55296
	ds_read_b128 v[222:225], v193 offset:56320
	global_load_lds_dwordx4 v[212:213], off
	v_lshl_add_u64 v[212:213], v[214:215], 0, s[90:91]
	s_add_i32 m0, s12, 0x2000
	s_add_i32 s12, s37, s42
	global_load_lds_dwordx4 v[212:213], off
	v_lshl_add_u64 v[212:213], v[220:221], 0, s[90:91]
	s_mov_b32 m0, s12
	s_nop 0
	global_load_lds_dwordx4 v[212:213], off
	v_lshl_add_u64 v[212:213], v[226:227], 0, s[90:91]
	s_add_i32 m0, s12, 0x2000
	s_nop 0
	global_load_lds_dwordx4 v[212:213], off
	v_lshl_add_u64 v[212:213], s[2:3], 0, v[130:131]
	s_mov_b32 m0, s52
	s_nop 0
	global_load_lds_dwordx4 v[212:213], off
	v_lshl_add_u64 v[212:213], s[2:3], 0, v[132:133]
	s_mov_b32 m0, s53
	s_nop 0
	global_load_lds_dwordx4 v[212:213], off
	s_waitcnt vmcnt(8)
	s_waitcnt lgkmcnt(0)
	s_barrier
	s_setprio 1
	s_waitcnt lgkmcnt(0)
	v_mfma_f32_16x16x32_bf16 v[60:63], v[136:139], v[174:177], v[60:63]
	v_mfma_f32_16x16x32_bf16 v[56:59], v[144:147], v[174:177], v[56:59]
	v_mfma_f32_16x16x32_bf16 v[44:47], v[136:139], v[182:185], v[44:47]
	v_mfma_f32_16x16x32_bf16 v[40:43], v[144:147], v[182:185], v[40:43]
	v_mfma_f32_16x16x32_bf16 v[28:31], v[136:139], v[194:197], v[28:31]
	v_mfma_f32_16x16x32_bf16 v[24:27], v[144:147], v[194:197], v[24:27]
	v_mfma_f32_16x16x32_bf16 v[12:15], v[136:139], v[202:205], v[12:15]
	v_mfma_f32_16x16x32_bf16 v[8:11], v[144:147], v[202:205], v[8:11]
	v_mfma_f32_16x16x32_bf16 v[60:63], v[140:143], v[178:181], v[60:63]
	v_mfma_f32_16x16x32_bf16 v[56:59], v[148:151], v[178:181], v[56:59]
	v_mfma_f32_16x16x32_bf16 v[44:47], v[140:143], v[186:189], v[44:47]
	v_mfma_f32_16x16x32_bf16 v[40:43], v[148:151], v[186:189], v[40:43]
	v_mfma_f32_16x16x32_bf16 v[28:31], v[140:143], v[198:201], v[28:31]
	v_mfma_f32_16x16x32_bf16 v[24:27], v[148:151], v[198:201], v[24:27]
	v_mfma_f32_16x16x32_bf16 v[12:15], v[140:143], v[222:225], v[12:15]
	v_mfma_f32_16x16x32_bf16 v[8:11], v[148:151], v[222:225], v[8:11]
	s_setprio 0
	s_setprio 1
	v_mfma_f32_16x16x32_bf16 v[52:55], v[152:155], v[174:177], v[52:55]
	v_mfma_f32_16x16x32_bf16 v[48:51], v[160:163], v[174:177], v[48:51]
	v_mfma_f32_16x16x32_bf16 v[36:39], v[152:155], v[182:185], v[36:39]
	v_mfma_f32_16x16x32_bf16 v[32:35], v[160:163], v[182:185], v[32:35]
	v_mfma_f32_16x16x32_bf16 v[20:23], v[152:155], v[194:197], v[20:23]
	v_mfma_f32_16x16x32_bf16 v[16:19], v[160:163], v[194:197], v[16:19]
	v_mfma_f32_16x16x32_bf16 v[4:7], v[152:155], v[202:205], v[4:7]
	v_mfma_f32_16x16x32_bf16 v[0:3], v[160:163], v[202:205], v[0:3]
	v_mfma_f32_16x16x32_bf16 v[52:55], v[156:159], v[178:181], v[52:55]
	v_mfma_f32_16x16x32_bf16 v[48:51], v[164:167], v[178:181], v[48:51]
	v_mfma_f32_16x16x32_bf16 v[36:39], v[156:159], v[186:189], v[36:39]
	v_mfma_f32_16x16x32_bf16 v[32:35], v[164:167], v[186:189], v[32:35]
	v_mfma_f32_16x16x32_bf16 v[20:23], v[156:159], v[198:201], v[20:23]
	v_mfma_f32_16x16x32_bf16 v[16:19], v[164:167], v[198:201], v[16:19]
	v_mfma_f32_16x16x32_bf16 v[4:7], v[156:159], v[222:225], v[4:7]
	v_mfma_f32_16x16x32_bf16 v[0:3], v[164:167], v[222:225], v[0:3]
	s_setprio 0
	s_barrier
	s_mov_b32 s101, 0
	s_add_u32 s63, s63, 0x100
	s_addc_u32 s64, s64, 0
	s_cmp_ge_u32 s10, s47
	s_mov_b64 s[2:3], s[10:11]
	s_cbranch_scc0 .LBB0_944
	s_and_b64 vcc, exec, s[28:29]
	s_cbranch_vccz .LBB0_947
	s_barrier
.LBB0_947:
	s_lshl_b32 s2, s19, 8
	s_mov_b64 s[12:13], s[26:27]
	v_readlane_b32 s0, v251, 20
	v_readlane_b32 s1, v251, 21
	v_and_b32_e32 v140, 0x60, v191
	v_and_b32_e32 v141, 16, v209
	v_and_b32_e32 v142, 32, v209
	v_lshrrev_b32_e32 v142, 2, v142
	v_or3_b32 v140, v140, v141, v142
	v_lshl_or_b32 v140, s18, 8, v140
	v_add_u32_e32 v141, s2, v173
	v_lshlrev_b32_e32 v142, 11, v141
	v_lshl_add_u32 v136, v140, 1, v142
	v_lshlrev_b32_e32 v142, 12, v141
	v_lshl_add_u32 v137, v140, 2, v142
	v_xor_b32_e32 v138, 16, v209
	v_xor_b32_e32 v139, 32, v209
	v_lshlrev_b32_e32 v138, 2, v138
	v_lshlrev_b32_e32 v139, 2, v139
	s_and_b64 vcc, exec, s[26:27]
	s_cbranch_vccnz .Lresid_fin
	s_add_u32 s10, s0, 0x0
	s_addc_u32 s11, s1, 0
	global_load_dwordx4 v[140:143], v136, s[10:11]
	global_load_dwordx4 v[144:147], v136, s[10:11] offset:256
	s_add_u32 s10, s0, 0x8000
	s_addc_u32 s11, s1, 0
	global_load_dwordx4 v[148:151], v136, s[10:11]
	global_load_dwordx4 v[152:155], v136, s[10:11] offset:256
	s_add_u32 s10, s0, 0x10000
	s_addc_u32 s11, s1, 0
	global_load_dwordx4 v[156:159], v136, s[10:11]
	global_load_dwordx4 v[160:163], v136, s[10:11] offset:256
	s_add_u32 s10, s0, 0x18000
	s_addc_u32 s11, s1, 0
	global_load_dwordx4 v[164:167], v136, s[10:11]
	global_load_dwordx4 v[174:177], v136, s[10:11] offset:256
	s_waitcnt vmcnt(7)
	v_permlane16_swap_b32_e32 v126, v122
	v_permlane16_swap_b32_e32 v127, v123
	v_permlane16_swap_b32_e32 v128, v124
	v_permlane16_swap_b32_e32 v129, v125
	v_lshlrev_b32_e32 v178, 16, v140
	v_and_b32_e32 v179, 0xffff0000, v140
	v_lshlrev_b32_e32 v180, 16, v141
	v_and_b32_e32 v181, 0xffff0000, v141
	v_lshlrev_b32_e32 v182, 16, v142
	v_and_b32_e32 v183, 0xffff0000, v142
	v_lshlrev_b32_e32 v184, 16, v143
	v_and_b32_e32 v185, 0xffff0000, v143
	v_pk_fma_f32 v[126:127], s[14:15], v[126:127], v[178:179]
	v_pk_fma_f32 v[128:129], s[14:15], v[128:129], v[180:181]
	v_pk_fma_f32 v[122:123], s[14:15], v[122:123], v[182:183]
	v_pk_fma_f32 v[124:125], s[14:15], v[124:125], v[184:185]
	s_add_u32 s10, s0, 0x0
	s_addc_u32 s11, s1, 0
	v_cvt_pk_bf16_f32 v140, v126, v127
	v_cvt_pk_bf16_f32 v141, v128, v129
	v_cvt_pk_bf16_f32 v142, v122, v123
	v_cvt_pk_bf16_f32 v143, v124, v125
	global_store_dwordx4 v136, v[140:143], s[10:11]
	s_add_u32 s10, s0, 0x40000
	s_addc_u32 s11, s1, 0
	global_load_dwordx4 v[126:129], v136, s[10:11]
	v_lshlrev_b32_e32 v178, 16, v140
	v_lshlrev_b32_e32 v179, 16, v141
	v_and_b32_e32 v180, 0xffff0000, v140
	v_and_b32_e32 v181, 0xffff0000, v141
	v_lshlrev_b32_e32 v182, 16, v142
	v_lshlrev_b32_e32 v183, 16, v143
	v_and_b32_e32 v184, 0xffff0000, v142
	v_and_b32_e32 v185, 0xffff0000, v143
	v_pk_mul_f32 v[180:181], v[180:181], v[180:181]
	v_pk_mul_f32 v[184:185], v[184:185], v[184:185]
	v_pk_fma_f32 v[178:179], v[178:179], v[178:179], v[180:181]
	v_pk_fma_f32 v[182:183], v[182:183], v[182:183], v[184:185]
	s_nop 0
	v_add_f32_e32 v178, v178, v179
	v_add_f32_e32 v182, v182, v183
	v_add_f32_e32 v186, v178, v182
	s_waitcnt vmcnt(8)
	v_permlane16_swap_b32_e32 v118, v114
	v_permlane16_swap_b32_e32 v119, v115
	v_permlane16_swap_b32_e32 v120, v116
	v_permlane16_swap_b32_e32 v121, v117
	v_lshlrev_b32_e32 v178, 16, v144
	v_and_b32_e32 v179, 0xffff0000, v144
	v_lshlrev_b32_e32 v180, 16, v145
	v_and_b32_e32 v181, 0xffff0000, v145
	v_lshlrev_b32_e32 v182, 16, v146
	v_and_b32_e32 v183, 0xffff0000, v146
	v_lshlrev_b32_e32 v184, 16, v147
	v_and_b32_e32 v185, 0xffff0000, v147
	v_pk_fma_f32 v[118:119], s[14:15], v[118:119], v[178:179]
	v_pk_fma_f32 v[120:121], s[14:15], v[120:121], v[180:181]
	v_pk_fma_f32 v[114:115], s[14:15], v[114:115], v[182:183]
	v_pk_fma_f32 v[116:117], s[14:15], v[116:117], v[184:185]
	s_add_u32 s10, s0, 0x0
	s_addc_u32 s11, s1, 0
	v_cvt_pk_bf16_f32 v144, v118, v119
	v_cvt_pk_bf16_f32 v145, v120, v121
	v_cvt_pk_bf16_f32 v146, v114, v115
	v_cvt_pk_bf16_f32 v147, v116, v117
	global_store_dwordx4 v136, v[144:147], s[10:11] offset:256
	s_add_u32 s10, s0, 0x40000
	s_addc_u32 s11, s1, 0
	global_load_dwordx4 v[118:121], v136, s[10:11] offset:256
	v_lshlrev_b32_e32 v178, 16, v144
	v_lshlrev_b32_e32 v179, 16, v145
	v_and_b32_e32 v180, 0xffff0000, v144
	v_and_b32_e32 v181, 0xffff0000, v145
	v_lshlrev_b32_e32 v182, 16, v146
	v_lshlrev_b32_e32 v183, 16, v147
	v_and_b32_e32 v184, 0xffff0000, v146
	v_and_b32_e32 v185, 0xffff0000, v147
	v_pk_mul_f32 v[180:181], v[180:181], v[180:181]
	v_pk_mul_f32 v[184:185], v[184:185], v[184:185]
	v_pk_fma_f32 v[178:179], v[178:179], v[178:179], v[180:181]
	v_pk_fma_f32 v[182:183], v[182:183], v[182:183], v[184:185]
	s_nop 0
	v_add_f32_e32 v178, v178, v179
	v_add_f32_e32 v182, v182, v183
	v_add_f32_e32 v186, v186, v178
	v_add_f32_e32 v186, v186, v182
	s_waitcnt vmcnt(9)
	v_permlane16_swap_b32_e32 v110, v106
	v_permlane16_swap_b32_e32 v111, v107
	v_permlane16_swap_b32_e32 v112, v108
	v_permlane16_swap_b32_e32 v113, v109
	v_lshlrev_b32_e32 v178, 16, v148
	v_and_b32_e32 v179, 0xffff0000, v148
	v_lshlrev_b32_e32 v180, 16, v149
	v_and_b32_e32 v181, 0xffff0000, v149
	v_lshlrev_b32_e32 v182, 16, v150
	v_and_b32_e32 v183, 0xffff0000, v150
	v_lshlrev_b32_e32 v184, 16, v151
	v_and_b32_e32 v185, 0xffff0000, v151
	v_pk_fma_f32 v[110:111], s[14:15], v[110:111], v[178:179]
	v_pk_fma_f32 v[112:113], s[14:15], v[112:113], v[180:181]
	v_pk_fma_f32 v[106:107], s[14:15], v[106:107], v[182:183]
	v_pk_fma_f32 v[108:109], s[14:15], v[108:109], v[184:185]
	s_add_u32 s10, s0, 0x8000
	s_addc_u32 s11, s1, 0
	v_cvt_pk_bf16_f32 v148, v110, v111
	v_cvt_pk_bf16_f32 v149, v112, v113
	v_cvt_pk_bf16_f32 v150, v106, v107
	v_cvt_pk_bf16_f32 v151, v108, v109
	global_store_dwordx4 v136, v[148:151], s[10:11]
	s_add_u32 s10, s0, 0x48000
	s_addc_u32 s11, s1, 0
	global_load_dwordx4 v[110:113], v136, s[10:11]
	v_lshlrev_b32_e32 v178, 16, v148
	v_lshlrev_b32_e32 v179, 16, v149
	v_and_b32_e32 v180, 0xffff0000, v148
	v_and_b32_e32 v181, 0xffff0000, v149
	v_lshlrev_b32_e32 v182, 16, v150
	v_lshlrev_b32_e32 v183, 16, v151
	v_and_b32_e32 v184, 0xffff0000, v150
	v_and_b32_e32 v185, 0xffff0000, v151
	v_pk_mul_f32 v[180:181], v[180:181], v[180:181]
	v_pk_mul_f32 v[184:185], v[184:185], v[184:185]
	v_pk_fma_f32 v[178:179], v[178:179], v[178:179], v[180:181]
	v_pk_fma_f32 v[182:183], v[182:183], v[182:183], v[184:185]
	s_nop 0
	v_add_f32_e32 v178, v178, v179
	v_add_f32_e32 v182, v182, v183
	v_add_f32_e32 v187, v178, v182
	s_waitcnt vmcnt(10)
	v_permlane16_swap_b32_e32 v102, v98
	v_permlane16_swap_b32_e32 v103, v99
	v_permlane16_swap_b32_e32 v104, v100
	v_permlane16_swap_b32_e32 v105, v101
	v_lshlrev_b32_e32 v178, 16, v152
	v_and_b32_e32 v179, 0xffff0000, v152
	v_lshlrev_b32_e32 v180, 16, v153
	v_and_b32_e32 v181, 0xffff0000, v153
	v_lshlrev_b32_e32 v182, 16, v154
	v_and_b32_e32 v183, 0xffff0000, v154
	v_lshlrev_b32_e32 v184, 16, v155
	v_and_b32_e32 v185, 0xffff0000, v155
	v_pk_fma_f32 v[102:103], s[14:15], v[102:103], v[178:179]
	v_pk_fma_f32 v[104:105], s[14:15], v[104:105], v[180:181]
	v_pk_fma_f32 v[98:99], s[14:15], v[98:99], v[182:183]
	v_pk_fma_f32 v[100:101], s[14:15], v[100:101], v[184:185]
	s_add_u32 s10, s0, 0x8000
	s_addc_u32 s11, s1, 0
	v_cvt_pk_bf16_f32 v152, v102, v103
	v_cvt_pk_bf16_f32 v153, v104, v105
	v_cvt_pk_bf16_f32 v154, v98, v99
	v_cvt_pk_bf16_f32 v155, v100, v101
	global_store_dwordx4 v136, v[152:155], s[10:11] offset:256
	s_add_u32 s10, s0, 0x48000
	s_addc_u32 s11, s1, 0
	global_load_dwordx4 v[102:105], v136, s[10:11] offset:256
	v_lshlrev_b32_e32 v178, 16, v152
	v_lshlrev_b32_e32 v179, 16, v153
	v_and_b32_e32 v180, 0xffff0000, v152
	v_and_b32_e32 v181, 0xffff0000, v153
	v_lshlrev_b32_e32 v182, 16, v154
	v_lshlrev_b32_e32 v183, 16, v155
	v_and_b32_e32 v184, 0xffff0000, v154
	v_and_b32_e32 v185, 0xffff0000, v155
	v_pk_mul_f32 v[180:181], v[180:181], v[180:181]
	v_pk_mul_f32 v[184:185], v[184:185], v[184:185]
	v_pk_fma_f32 v[178:179], v[178:179], v[178:179], v[180:181]
	v_pk_fma_f32 v[182:183], v[182:183], v[182:183], v[184:185]
	s_nop 0
	v_add_f32_e32 v178, v178, v179
	v_add_f32_e32 v182, v182, v183
	v_add_f32_e32 v187, v187, v178
	v_add_f32_e32 v187, v187, v182
	s_waitcnt vmcnt(11)
	v_permlane16_swap_b32_e32 v92, v88
	v_permlane16_swap_b32_e32 v93, v89
	v_permlane16_swap_b32_e32 v94, v90
	v_permlane16_swap_b32_e32 v95, v91
	v_lshlrev_b32_e32 v178, 16, v156
	v_and_b32_e32 v179, 0xffff0000, v156
	v_lshlrev_b32_e32 v180, 16, v157
	v_and_b32_e32 v181, 0xffff0000, v157
	v_lshlrev_b32_e32 v182, 16, v158
	v_and_b32_e32 v183, 0xffff0000, v158
	v_lshlrev_b32_e32 v184, 16, v159
	v_and_b32_e32 v185, 0xffff0000, v159
	v_pk_fma_f32 v[92:93], s[14:15], v[92:93], v[178:179]
	v_pk_fma_f32 v[94:95], s[14:15], v[94:95], v[180:181]
	v_pk_fma_f32 v[88:89], s[14:15], v[88:89], v[182:183]
	v_pk_fma_f32 v[90:91], s[14:15], v[90:91], v[184:185]
	s_add_u32 s10, s0, 0x10000
	s_addc_u32 s11, s1, 0
	v_cvt_pk_bf16_f32 v156, v92, v93
	v_cvt_pk_bf16_f32 v157, v94, v95
	v_cvt_pk_bf16_f32 v158, v88, v89
	v_cvt_pk_bf16_f32 v159, v90, v91
	global_store_dwordx4 v136, v[156:159], s[10:11]
	s_add_u32 s10, s0, 0x50000
	s_addc_u32 s11, s1, 0
	global_load_dwordx4 v[92:95], v136, s[10:11]
	v_lshlrev_b32_e32 v178, 16, v156
	v_lshlrev_b32_e32 v179, 16, v157
	v_and_b32_e32 v180, 0xffff0000, v156
	v_and_b32_e32 v181, 0xffff0000, v157
	v_lshlrev_b32_e32 v182, 16, v158
	v_lshlrev_b32_e32 v183, 16, v159
	v_and_b32_e32 v184, 0xffff0000, v158
	v_and_b32_e32 v185, 0xffff0000, v159
	v_pk_mul_f32 v[180:181], v[180:181], v[180:181]
	v_pk_mul_f32 v[184:185], v[184:185], v[184:185]
	v_pk_fma_f32 v[178:179], v[178:179], v[178:179], v[180:181]
	v_pk_fma_f32 v[182:183], v[182:183], v[182:183], v[184:185]
	s_nop 0
	v_add_f32_e32 v178, v178, v179
	v_add_f32_e32 v182, v182, v183
	v_add_f32_e32 v188, v178, v182
	s_waitcnt vmcnt(12)
	v_permlane16_swap_b32_e32 v84, v80
	v_permlane16_swap_b32_e32 v85, v81
	v_permlane16_swap_b32_e32 v86, v82
	v_permlane16_swap_b32_e32 v87, v83
	v_lshlrev_b32_e32 v178, 16, v160
	v_and_b32_e32 v179, 0xffff0000, v160
	v_lshlrev_b32_e32 v180, 16, v161
	v_and_b32_e32 v181, 0xffff0000, v161
	v_lshlrev_b32_e32 v182, 16, v162
	v_and_b32_e32 v183, 0xffff0000, v162
	v_lshlrev_b32_e32 v184, 16, v163
	v_and_b32_e32 v185, 0xffff0000, v163
	v_pk_fma_f32 v[84:85], s[14:15], v[84:85], v[178:179]
	v_pk_fma_f32 v[86:87], s[14:15], v[86:87], v[180:181]
	v_pk_fma_f32 v[80:81], s[14:15], v[80:81], v[182:183]
	v_pk_fma_f32 v[82:83], s[14:15], v[82:83], v[184:185]
	s_add_u32 s10, s0, 0x10000
	s_addc_u32 s11, s1, 0
	v_cvt_pk_bf16_f32 v160, v84, v85
	v_cvt_pk_bf16_f32 v161, v86, v87
	v_cvt_pk_bf16_f32 v162, v80, v81
	v_cvt_pk_bf16_f32 v163, v82, v83
	global_store_dwordx4 v136, v[160:163], s[10:11] offset:256
	s_add_u32 s10, s0, 0x50000
	s_addc_u32 s11, s1, 0
	global_load_dwordx4 v[84:87], v136, s[10:11] offset:256
	v_lshlrev_b32_e32 v178, 16, v160
	v_lshlrev_b32_e32 v179, 16, v161
	v_and_b32_e32 v180, 0xffff0000, v160
	v_and_b32_e32 v181, 0xffff0000, v161
	v_lshlrev_b32_e32 v182, 16, v162
	v_lshlrev_b32_e32 v183, 16, v163
	v_and_b32_e32 v184, 0xffff0000, v162
	v_and_b32_e32 v185, 0xffff0000, v163
	v_pk_mul_f32 v[180:181], v[180:181], v[180:181]
	v_pk_mul_f32 v[184:185], v[184:185], v[184:185]
	v_pk_fma_f32 v[178:179], v[178:179], v[178:179], v[180:181]
	v_pk_fma_f32 v[182:183], v[182:183], v[182:183], v[184:185]
	s_nop 0
	v_add_f32_e32 v178, v178, v179
	v_add_f32_e32 v182, v182, v183
	v_add_f32_e32 v188, v188, v178
	v_add_f32_e32 v188, v188, v182
	s_waitcnt vmcnt(13)
	v_permlane16_swap_b32_e32 v76, v72
	v_permlane16_swap_b32_e32 v77, v73
	v_permlane16_swap_b32_e32 v78, v74
	v_permlane16_swap_b32_e32 v79, v75
	v_lshlrev_b32_e32 v178, 16, v164
	v_and_b32_e32 v179, 0xffff0000, v164
	v_lshlrev_b32_e32 v180, 16, v165
	v_and_b32_e32 v181, 0xffff0000, v165
	v_lshlrev_b32_e32 v182, 16, v166
	v_and_b32_e32 v183, 0xffff0000, v166
	v_lshlrev_b32_e32 v184, 16, v167
	v_and_b32_e32 v185, 0xffff0000, v167
	v_pk_fma_f32 v[76:77], s[14:15], v[76:77], v[178:179]
	v_pk_fma_f32 v[78:79], s[14:15], v[78:79], v[180:181]
	v_pk_fma_f32 v[72:73], s[14:15], v[72:73], v[182:183]
	v_pk_fma_f32 v[74:75], s[14:15], v[74:75], v[184:185]
	s_add_u32 s10, s0, 0x18000
	s_addc_u32 s11, s1, 0
	v_cvt_pk_bf16_f32 v164, v76, v77
	v_cvt_pk_bf16_f32 v165, v78, v79
	v_cvt_pk_bf16_f32 v166, v72, v73
	v_cvt_pk_bf16_f32 v167, v74, v75
	global_store_dwordx4 v136, v[164:167], s[10:11]
	s_add_u32 s10, s0, 0x58000
	s_addc_u32 s11, s1, 0
	global_load_dwordx4 v[76:79], v136, s[10:11]
	v_lshlrev_b32_e32 v178, 16, v164
	v_lshlrev_b32_e32 v179, 16, v165
	v_and_b32_e32 v180, 0xffff0000, v164
	v_and_b32_e32 v181, 0xffff0000, v165
	v_lshlrev_b32_e32 v182, 16, v166
	v_lshlrev_b32_e32 v183, 16, v167
	v_and_b32_e32 v184, 0xffff0000, v166
	v_and_b32_e32 v185, 0xffff0000, v167
	v_pk_mul_f32 v[180:181], v[180:181], v[180:181]
	v_pk_mul_f32 v[184:185], v[184:185], v[184:185]
	v_pk_fma_f32 v[178:179], v[178:179], v[178:179], v[180:181]
	v_pk_fma_f32 v[182:183], v[182:183], v[182:183], v[184:185]
	s_nop 0
	v_add_f32_e32 v178, v178, v179
	v_add_f32_e32 v182, v182, v183
	v_add_f32_e32 v189, v178, v182
	s_waitcnt vmcnt(14)
	v_permlane16_swap_b32_e32 v68, v64
	v_permlane16_swap_b32_e32 v69, v65
	v_permlane16_swap_b32_e32 v70, v66
	v_permlane16_swap_b32_e32 v71, v67
	v_lshlrev_b32_e32 v178, 16, v174
	v_and_b32_e32 v179, 0xffff0000, v174
	v_lshlrev_b32_e32 v180, 16, v175
	v_and_b32_e32 v181, 0xffff0000, v175
	v_lshlrev_b32_e32 v182, 16, v176
	v_and_b32_e32 v183, 0xffff0000, v176
	v_lshlrev_b32_e32 v184, 16, v177
	v_and_b32_e32 v185, 0xffff0000, v177
	v_pk_fma_f32 v[68:69], s[14:15], v[68:69], v[178:179]
	v_pk_fma_f32 v[70:71], s[14:15], v[70:71], v[180:181]
	v_pk_fma_f32 v[64:65], s[14:15], v[64:65], v[182:183]
	v_pk_fma_f32 v[66:67], s[14:15], v[66:67], v[184:185]
	s_add_u32 s10, s0, 0x18000
	s_addc_u32 s11, s1, 0
	v_cvt_pk_bf16_f32 v174, v68, v69
	v_cvt_pk_bf16_f32 v175, v70, v71
	v_cvt_pk_bf16_f32 v176, v64, v65
	v_cvt_pk_bf16_f32 v177, v66, v67
	global_store_dwordx4 v136, v[174:177], s[10:11] offset:256
	s_add_u32 s10, s0, 0x58000
	s_addc_u32 s11, s1, 0
	global_load_dwordx4 v[68:71], v136, s[10:11] offset:256
	v_lshlrev_b32_e32 v178, 16, v174
	v_lshlrev_b32_e32 v179, 16, v175
	v_and_b32_e32 v180, 0xffff0000, v174
	v_and_b32_e32 v181, 0xffff0000, v175
	v_lshlrev_b32_e32 v182, 16, v176
	v_lshlrev_b32_e32 v183, 16, v177
	v_and_b32_e32 v184, 0xffff0000, v176
	v_and_b32_e32 v185, 0xffff0000, v177
	v_pk_mul_f32 v[180:181], v[180:181], v[180:181]
	v_pk_mul_f32 v[184:185], v[184:185], v[184:185]
	v_pk_fma_f32 v[178:179], v[178:179], v[178:179], v[180:181]
	v_pk_fma_f32 v[182:183], v[182:183], v[182:183], v[184:185]
	s_nop 0
	v_add_f32_e32 v178, v178, v179
	v_add_f32_e32 v182, v182, v183
	v_add_f32_e32 v189, v189, v178
	v_add_f32_e32 v189, v189, v182
	ds_bpermute_b32 v178, v138, v186
	ds_bpermute_b32 v179, v138, v187
	ds_bpermute_b32 v180, v138, v188
	ds_bpermute_b32 v181, v138, v189
	s_waitcnt lgkmcnt(0)
	v_add_f32_e32 v186, v186, v178
	v_add_f32_e32 v187, v187, v179
	v_add_f32_e32 v188, v188, v180
	v_add_f32_e32 v189, v189, v181
	ds_bpermute_b32 v178, v139, v186
	ds_bpermute_b32 v179, v139, v187
	ds_bpermute_b32 v180, v139, v188
	ds_bpermute_b32 v181, v139, v189
	s_waitcnt lgkmcnt(0)
	v_add_f32_e32 v186, v186, v178
	v_add_f32_e32 v187, v187, v179
	v_add_f32_e32 v188, v188, v180
	v_add_f32_e32 v189, v189, v181
	s_and_saveexec_b64 vcc, s[4:5]
	ds_write_b32 v192, v186
	ds_write_b32 v192, v187 offset:256
	ds_write_b32 v192, v188 offset:512
	ds_write_b32 v192, v189 offset:768
	s_or_b64 exec, exec, vcc
	s_waitcnt vmcnt(14)
	v_permlane16_swap_b32_e32 v60, v56
	v_permlane16_swap_b32_e32 v61, v57
	v_permlane16_swap_b32_e32 v62, v58
	v_permlane16_swap_b32_e32 v63, v59
	v_lshlrev_b32_e32 v178, 16, v126
	v_and_b32_e32 v179, 0xffff0000, v126
	v_lshlrev_b32_e32 v180, 16, v127
	v_and_b32_e32 v181, 0xffff0000, v127
	v_lshlrev_b32_e32 v182, 16, v128
	v_and_b32_e32 v183, 0xffff0000, v128
	v_lshlrev_b32_e32 v184, 16, v129
	v_and_b32_e32 v185, 0xffff0000, v129
	v_pk_fma_f32 v[60:61], s[14:15], v[60:61], v[178:179]
	v_pk_fma_f32 v[62:63], s[14:15], v[62:63], v[180:181]
	v_pk_fma_f32 v[56:57], s[14:15], v[56:57], v[182:183]
	v_pk_fma_f32 v[58:59], s[14:15], v[58:59], v[184:185]
	s_add_u32 s10, s0, 0x40000
	s_addc_u32 s11, s1, 0
	v_cvt_pk_bf16_f32 v126, v60, v61
	v_cvt_pk_bf16_f32 v127, v62, v63
	v_cvt_pk_bf16_f32 v128, v56, v57
	v_cvt_pk_bf16_f32 v129, v58, v59
	global_store_dwordx4 v136, v[126:129], s[10:11]
	v_lshlrev_b32_e32 v178, 16, v126
	v_lshlrev_b32_e32 v179, 16, v127
	v_and_b32_e32 v180, 0xffff0000, v126
	v_and_b32_e32 v181, 0xffff0000, v127
	v_lshlrev_b32_e32 v182, 16, v128
	v_lshlrev_b32_e32 v183, 16, v129
	v_and_b32_e32 v184, 0xffff0000, v128
	v_and_b32_e32 v185, 0xffff0000, v129
	v_pk_mul_f32 v[180:181], v[180:181], v[180:181]
	v_pk_mul_f32 v[184:185], v[184:185], v[184:185]
	v_pk_fma_f32 v[178:179], v[178:179], v[178:179], v[180:181]
	v_pk_fma_f32 v[182:183], v[182:183], v[182:183], v[184:185]
	s_nop 0
	v_add_f32_e32 v178, v178, v179
	v_add_f32_e32 v182, v182, v183
	v_add_f32_e32 v186, v178, v182
	s_waitcnt vmcnt(13)
	v_permlane16_swap_b32_e32 v52, v48
	v_permlane16_swap_b32_e32 v53, v49
	v_permlane16_swap_b32_e32 v54, v50
	v_permlane16_swap_b32_e32 v55, v51
	v_lshlrev_b32_e32 v178, 16, v118
	v_and_b32_e32 v179, 0xffff0000, v118
	v_lshlrev_b32_e32 v180, 16, v119
	v_and_b32_e32 v181, 0xffff0000, v119
	v_lshlrev_b32_e32 v182, 16, v120
	v_and_b32_e32 v183, 0xffff0000, v120
	v_lshlrev_b32_e32 v184, 16, v121
	v_and_b32_e32 v185, 0xffff0000, v121
	v_pk_fma_f32 v[52:53], s[14:15], v[52:53], v[178:179]
	v_pk_fma_f32 v[54:55], s[14:15], v[54:55], v[180:181]
	v_pk_fma_f32 v[48:49], s[14:15], v[48:49], v[182:183]
	v_pk_fma_f32 v[50:51], s[14:15], v[50:51], v[184:185]
	s_add_u32 s10, s0, 0x40000
	s_addc_u32 s11, s1, 0
	v_cvt_pk_bf16_f32 v118, v52, v53
	v_cvt_pk_bf16_f32 v119, v54, v55
	v_cvt_pk_bf16_f32 v120, v48, v49
	v_cvt_pk_bf16_f32 v121, v50, v51
	global_store_dwordx4 v136, v[118:121], s[10:11] offset:256
	v_lshlrev_b32_e32 v178, 16, v118
	v_lshlrev_b32_e32 v179, 16, v119
	v_and_b32_e32 v180, 0xffff0000, v118
	v_and_b32_e32 v181, 0xffff0000, v119
	v_lshlrev_b32_e32 v182, 16, v120
	v_lshlrev_b32_e32 v183, 16, v121
	v_and_b32_e32 v184, 0xffff0000, v120
	v_and_b32_e32 v185, 0xffff0000, v121
	v_pk_mul_f32 v[180:181], v[180:181], v[180:181]
	v_pk_mul_f32 v[184:185], v[184:185], v[184:185]
	v_pk_fma_f32 v[178:179], v[178:179], v[178:179], v[180:181]
	v_pk_fma_f32 v[182:183], v[182:183], v[182:183], v[184:185]
	s_nop 0
	v_add_f32_e32 v178, v178, v179
	v_add_f32_e32 v182, v182, v183
	v_add_f32_e32 v186, v186, v178
	v_add_f32_e32 v186, v186, v182
	s_waitcnt vmcnt(12)
	v_permlane16_swap_b32_e32 v44, v40
	v_permlane16_swap_b32_e32 v45, v41
	v_permlane16_swap_b32_e32 v46, v42
	v_permlane16_swap_b32_e32 v47, v43
	v_lshlrev_b32_e32 v178, 16, v110
	v_and_b32_e32 v179, 0xffff0000, v110
	v_lshlrev_b32_e32 v180, 16, v111
	v_and_b32_e32 v181, 0xffff0000, v111
	v_lshlrev_b32_e32 v182, 16, v112
	v_and_b32_e32 v183, 0xffff0000, v112
	v_lshlrev_b32_e32 v184, 16, v113
	v_and_b32_e32 v185, 0xffff0000, v113
	v_pk_fma_f32 v[44:45], s[14:15], v[44:45], v[178:179]
	v_pk_fma_f32 v[46:47], s[14:15], v[46:47], v[180:181]
	v_pk_fma_f32 v[40:41], s[14:15], v[40:41], v[182:183]
	v_pk_fma_f32 v[42:43], s[14:15], v[42:43], v[184:185]
	s_add_u32 s10, s0, 0x48000
	s_addc_u32 s11, s1, 0
	v_cvt_pk_bf16_f32 v110, v44, v45
	v_cvt_pk_bf16_f32 v111, v46, v47
	v_cvt_pk_bf16_f32 v112, v40, v41
	v_cvt_pk_bf16_f32 v113, v42, v43
	global_store_dwordx4 v136, v[110:113], s[10:11]
	v_lshlrev_b32_e32 v178, 16, v110
	v_lshlrev_b32_e32 v179, 16, v111
	v_and_b32_e32 v180, 0xffff0000, v110
	v_and_b32_e32 v181, 0xffff0000, v111
	v_lshlrev_b32_e32 v182, 16, v112
	v_lshlrev_b32_e32 v183, 16, v113
	v_and_b32_e32 v184, 0xffff0000, v112
	v_and_b32_e32 v185, 0xffff0000, v113
	v_pk_mul_f32 v[180:181], v[180:181], v[180:181]
	v_pk_mul_f32 v[184:185], v[184:185], v[184:185]
	v_pk_fma_f32 v[178:179], v[178:179], v[178:179], v[180:181]
	v_pk_fma_f32 v[182:183], v[182:183], v[182:183], v[184:185]
	s_nop 0
	v_add_f32_e32 v178, v178, v179
	v_add_f32_e32 v182, v182, v183
	v_add_f32_e32 v187, v178, v182
	s_waitcnt vmcnt(11)
	v_permlane16_swap_b32_e32 v36, v32
	v_permlane16_swap_b32_e32 v37, v33
	v_permlane16_swap_b32_e32 v38, v34
	v_permlane16_swap_b32_e32 v39, v35
	v_lshlrev_b32_e32 v178, 16, v102
	v_and_b32_e32 v179, 0xffff0000, v102
	v_lshlrev_b32_e32 v180, 16, v103
	v_and_b32_e32 v181, 0xffff0000, v103
	v_lshlrev_b32_e32 v182, 16, v104
	v_and_b32_e32 v183, 0xffff0000, v104
	v_lshlrev_b32_e32 v184, 16, v105
	v_and_b32_e32 v185, 0xffff0000, v105
	v_pk_fma_f32 v[36:37], s[14:15], v[36:37], v[178:179]
	v_pk_fma_f32 v[38:39], s[14:15], v[38:39], v[180:181]
	v_pk_fma_f32 v[32:33], s[14:15], v[32:33], v[182:183]
	v_pk_fma_f32 v[34:35], s[14:15], v[34:35], v[184:185]
	s_add_u32 s10, s0, 0x48000
	s_addc_u32 s11, s1, 0
	v_cvt_pk_bf16_f32 v102, v36, v37
	v_cvt_pk_bf16_f32 v103, v38, v39
	v_cvt_pk_bf16_f32 v104, v32, v33
	v_cvt_pk_bf16_f32 v105, v34, v35
	global_store_dwordx4 v136, v[102:105], s[10:11] offset:256
	v_lshlrev_b32_e32 v178, 16, v102
	v_lshlrev_b32_e32 v179, 16, v103
	v_and_b32_e32 v180, 0xffff0000, v102
	v_and_b32_e32 v181, 0xffff0000, v103
	v_lshlrev_b32_e32 v182, 16, v104
	v_lshlrev_b32_e32 v183, 16, v105
	v_and_b32_e32 v184, 0xffff0000, v104
	v_and_b32_e32 v185, 0xffff0000, v105
	v_pk_mul_f32 v[180:181], v[180:181], v[180:181]
	v_pk_mul_f32 v[184:185], v[184:185], v[184:185]
	v_pk_fma_f32 v[178:179], v[178:179], v[178:179], v[180:181]
	v_pk_fma_f32 v[182:183], v[182:183], v[182:183], v[184:185]
	s_nop 0
	v_add_f32_e32 v178, v178, v179
	v_add_f32_e32 v182, v182, v183
	v_add_f32_e32 v187, v187, v178
	v_add_f32_e32 v187, v187, v182
	s_waitcnt vmcnt(10)
	v_permlane16_swap_b32_e32 v28, v24
	v_permlane16_swap_b32_e32 v29, v25
	v_permlane16_swap_b32_e32 v30, v26
	v_permlane16_swap_b32_e32 v31, v27
	v_lshlrev_b32_e32 v178, 16, v92
	v_and_b32_e32 v179, 0xffff0000, v92
	v_lshlrev_b32_e32 v180, 16, v93
	v_and_b32_e32 v181, 0xffff0000, v93
	v_lshlrev_b32_e32 v182, 16, v94
	v_and_b32_e32 v183, 0xffff0000, v94
	v_lshlrev_b32_e32 v184, 16, v95
	v_and_b32_e32 v185, 0xffff0000, v95
	v_pk_fma_f32 v[28:29], s[14:15], v[28:29], v[178:179]
	v_pk_fma_f32 v[30:31], s[14:15], v[30:31], v[180:181]
	v_pk_fma_f32 v[24:25], s[14:15], v[24:25], v[182:183]
	v_pk_fma_f32 v[26:27], s[14:15], v[26:27], v[184:185]
	s_add_u32 s10, s0, 0x50000
	s_addc_u32 s11, s1, 0
	v_cvt_pk_bf16_f32 v92, v28, v29
	v_cvt_pk_bf16_f32 v93, v30, v31
	v_cvt_pk_bf16_f32 v94, v24, v25
	v_cvt_pk_bf16_f32 v95, v26, v27
	global_store_dwordx4 v136, v[92:95], s[10:11]
	v_lshlrev_b32_e32 v178, 16, v92
	v_lshlrev_b32_e32 v179, 16, v93
	v_and_b32_e32 v180, 0xffff0000, v92
	v_and_b32_e32 v181, 0xffff0000, v93
	v_lshlrev_b32_e32 v182, 16, v94
	v_lshlrev_b32_e32 v183, 16, v95
	v_and_b32_e32 v184, 0xffff0000, v94
	v_and_b32_e32 v185, 0xffff0000, v95
	v_pk_mul_f32 v[180:181], v[180:181], v[180:181]
	v_pk_mul_f32 v[184:185], v[184:185], v[184:185]
	v_pk_fma_f32 v[178:179], v[178:179], v[178:179], v[180:181]
	v_pk_fma_f32 v[182:183], v[182:183], v[182:183], v[184:185]
	s_nop 0
	v_add_f32_e32 v178, v178, v179
	v_add_f32_e32 v182, v182, v183
	v_add_f32_e32 v188, v178, v182
	s_waitcnt vmcnt(9)
	v_permlane16_swap_b32_e32 v20, v16
	v_permlane16_swap_b32_e32 v21, v17
	v_permlane16_swap_b32_e32 v22, v18
	v_permlane16_swap_b32_e32 v23, v19
	v_lshlrev_b32_e32 v178, 16, v84
	v_and_b32_e32 v179, 0xffff0000, v84
	v_lshlrev_b32_e32 v180, 16, v85
	v_and_b32_e32 v181, 0xffff0000, v85
	v_lshlrev_b32_e32 v182, 16, v86
	v_and_b32_e32 v183, 0xffff0000, v86
	v_lshlrev_b32_e32 v184, 16, v87
	v_and_b32_e32 v185, 0xffff0000, v87
	v_pk_fma_f32 v[20:21], s[14:15], v[20:21], v[178:179]
	v_pk_fma_f32 v[22:23], s[14:15], v[22:23], v[180:181]
	v_pk_fma_f32 v[16:17], s[14:15], v[16:17], v[182:183]
	v_pk_fma_f32 v[18:19], s[14:15], v[18:19], v[184:185]
	s_add_u32 s10, s0, 0x50000
	s_addc_u32 s11, s1, 0
	v_cvt_pk_bf16_f32 v84, v20, v21
	v_cvt_pk_bf16_f32 v85, v22, v23
	v_cvt_pk_bf16_f32 v86, v16, v17
	v_cvt_pk_bf16_f32 v87, v18, v19
	global_store_dwordx4 v136, v[84:87], s[10:11] offset:256
	v_lshlrev_b32_e32 v178, 16, v84
	v_lshlrev_b32_e32 v179, 16, v85
	v_and_b32_e32 v180, 0xffff0000, v84
	v_and_b32_e32 v181, 0xffff0000, v85
	v_lshlrev_b32_e32 v182, 16, v86
	v_lshlrev_b32_e32 v183, 16, v87
	v_and_b32_e32 v184, 0xffff0000, v86
	v_and_b32_e32 v185, 0xffff0000, v87
	v_pk_mul_f32 v[180:181], v[180:181], v[180:181]
	v_pk_mul_f32 v[184:185], v[184:185], v[184:185]
	v_pk_fma_f32 v[178:179], v[178:179], v[178:179], v[180:181]
	v_pk_fma_f32 v[182:183], v[182:183], v[182:183], v[184:185]
	s_nop 0
	v_add_f32_e32 v178, v178, v179
	v_add_f32_e32 v182, v182, v183
	v_add_f32_e32 v188, v188, v178
	v_add_f32_e32 v188, v188, v182
	s_waitcnt vmcnt(8)
	v_permlane16_swap_b32_e32 v12, v8
	v_permlane16_swap_b32_e32 v13, v9
	v_permlane16_swap_b32_e32 v14, v10
	v_permlane16_swap_b32_e32 v15, v11
	v_lshlrev_b32_e32 v178, 16, v76
	v_and_b32_e32 v179, 0xffff0000, v76
	v_lshlrev_b32_e32 v180, 16, v77
	v_and_b32_e32 v181, 0xffff0000, v77
	v_lshlrev_b32_e32 v182, 16, v78
	v_and_b32_e32 v183, 0xffff0000, v78
	v_lshlrev_b32_e32 v184, 16, v79
	v_and_b32_e32 v185, 0xffff0000, v79
	v_pk_fma_f32 v[12:13], s[14:15], v[12:13], v[178:179]
	v_pk_fma_f32 v[14:15], s[14:15], v[14:15], v[180:181]
	v_pk_fma_f32 v[8:9], s[14:15], v[8:9], v[182:183]
	v_pk_fma_f32 v[10:11], s[14:15], v[10:11], v[184:185]
	s_add_u32 s10, s0, 0x58000
	s_addc_u32 s11, s1, 0
	v_cvt_pk_bf16_f32 v76, v12, v13
	v_cvt_pk_bf16_f32 v77, v14, v15
	v_cvt_pk_bf16_f32 v78, v8, v9
	v_cvt_pk_bf16_f32 v79, v10, v11
	global_store_dwordx4 v136, v[76:79], s[10:11]
	v_lshlrev_b32_e32 v178, 16, v76
	v_lshlrev_b32_e32 v179, 16, v77
	v_and_b32_e32 v180, 0xffff0000, v76
	v_and_b32_e32 v181, 0xffff0000, v77
	v_lshlrev_b32_e32 v182, 16, v78
	v_lshlrev_b32_e32 v183, 16, v79
	v_and_b32_e32 v184, 0xffff0000, v78
	v_and_b32_e32 v185, 0xffff0000, v79
	v_pk_mul_f32 v[180:181], v[180:181], v[180:181]
	v_pk_mul_f32 v[184:185], v[184:185], v[184:185]
	v_pk_fma_f32 v[178:179], v[178:179], v[178:179], v[180:181]
	v_pk_fma_f32 v[182:183], v[182:183], v[182:183], v[184:185]
	s_nop 0
	v_add_f32_e32 v178, v178, v179
	v_add_f32_e32 v182, v182, v183
	v_add_f32_e32 v189, v178, v182
	s_waitcnt vmcnt(7)
	v_permlane16_swap_b32_e32 v4, v0
	v_permlane16_swap_b32_e32 v5, v1
	v_permlane16_swap_b32_e32 v6, v2
	v_permlane16_swap_b32_e32 v7, v3
	v_lshlrev_b32_e32 v178, 16, v68
	v_and_b32_e32 v179, 0xffff0000, v68
	v_lshlrev_b32_e32 v180, 16, v69
	v_and_b32_e32 v181, 0xffff0000, v69
	v_lshlrev_b32_e32 v182, 16, v70
	v_and_b32_e32 v183, 0xffff0000, v70
	v_lshlrev_b32_e32 v184, 16, v71
	v_and_b32_e32 v185, 0xffff0000, v71
	v_pk_fma_f32 v[4:5], s[14:15], v[4:5], v[178:179]
	v_pk_fma_f32 v[6:7], s[14:15], v[6:7], v[180:181]
	v_pk_fma_f32 v[0:1], s[14:15], v[0:1], v[182:183]
	v_pk_fma_f32 v[2:3], s[14:15], v[2:3], v[184:185]
	s_add_u32 s10, s0, 0x58000
	s_addc_u32 s11, s1, 0
	v_cvt_pk_bf16_f32 v68, v4, v5
	v_cvt_pk_bf16_f32 v69, v6, v7
	v_cvt_pk_bf16_f32 v70, v0, v1
	v_cvt_pk_bf16_f32 v71, v2, v3
	global_store_dwordx4 v136, v[68:71], s[10:11] offset:256
	v_lshlrev_b32_e32 v178, 16, v68
	v_lshlrev_b32_e32 v179, 16, v69
	v_and_b32_e32 v180, 0xffff0000, v68
	v_and_b32_e32 v181, 0xffff0000, v69
	v_lshlrev_b32_e32 v182, 16, v70
	v_lshlrev_b32_e32 v183, 16, v71
	v_and_b32_e32 v184, 0xffff0000, v70
	v_and_b32_e32 v185, 0xffff0000, v71
	v_pk_mul_f32 v[180:181], v[180:181], v[180:181]
	v_pk_mul_f32 v[184:185], v[184:185], v[184:185]
	v_pk_fma_f32 v[178:179], v[178:179], v[178:179], v[180:181]
	v_pk_fma_f32 v[182:183], v[182:183], v[182:183], v[184:185]
	s_nop 0
	v_add_f32_e32 v178, v178, v179
	v_add_f32_e32 v182, v182, v183
	v_add_f32_e32 v189, v189, v178
	v_add_f32_e32 v189, v189, v182
	ds_bpermute_b32 v178, v138, v186
	ds_bpermute_b32 v179, v138, v187
	ds_bpermute_b32 v180, v138, v188
	ds_bpermute_b32 v181, v138, v189
	s_waitcnt lgkmcnt(0)
	v_add_f32_e32 v186, v186, v178
	v_add_f32_e32 v187, v187, v179
	v_add_f32_e32 v188, v188, v180
	v_add_f32_e32 v189, v189, v181
	ds_bpermute_b32 v178, v139, v186
	ds_bpermute_b32 v179, v139, v187
	ds_bpermute_b32 v180, v139, v188
	ds_bpermute_b32 v181, v139, v189
	s_waitcnt lgkmcnt(0)
	v_add_f32_e32 v186, v186, v178
	v_add_f32_e32 v187, v187, v179
	v_add_f32_e32 v188, v188, v180
	v_add_f32_e32 v189, v189, v181
	s_and_saveexec_b64 vcc, s[4:5]
	ds_write_b32 v192, v186 offset:2048
	ds_write_b32 v192, v187 offset:2304
	ds_write_b32 v192, v188 offset:2560
	ds_write_b32 v192, v189 offset:2816
	s_or_b64 exec, exec, vcc
	s_mov_b32 s101, 1
	s_branch .LBB0_1107
.Lresid_fin:
	s_add_u32 s10, s0, 0x0
	s_addc_u32 s11, s1, 0
	global_load_dwordx4 v[140:143], v136, s[10:11]
	global_load_dwordx4 v[144:147], v136, s[10:11] offset:256
	s_add_u32 s10, s0, 0x8000
	s_addc_u32 s11, s1, 0
	global_load_dwordx4 v[148:151], v136, s[10:11]
	global_load_dwordx4 v[152:155], v136, s[10:11] offset:256
	s_add_u32 s10, s0, 0x10000
	s_addc_u32 s11, s1, 0
	global_load_dwordx4 v[156:159], v136, s[10:11]
	global_load_dwordx4 v[160:163], v136, s[10:11] offset:256
	s_add_u32 s10, s0, 0x18000
	s_addc_u32 s11, s1, 0
	global_load_dwordx4 v[164:167], v136, s[10:11]
	global_load_dwordx4 v[174:177], v136, s[10:11] offset:256
	s_waitcnt vmcnt(7)
	v_permlane16_swap_b32_e32 v126, v122
	v_permlane16_swap_b32_e32 v127, v123
	v_permlane16_swap_b32_e32 v128, v124
	v_permlane16_swap_b32_e32 v129, v125
	v_lshlrev_b32_e32 v178, 16, v140
	v_and_b32_e32 v179, 0xffff0000, v140
	v_lshlrev_b32_e32 v180, 16, v141
	v_and_b32_e32 v181, 0xffff0000, v141
	v_lshlrev_b32_e32 v182, 16, v142
	v_and_b32_e32 v183, 0xffff0000, v142
	v_lshlrev_b32_e32 v184, 16, v143
	v_and_b32_e32 v185, 0xffff0000, v143
	v_pk_fma_f32 v[126:127], s[14:15], v[126:127], v[178:179]
	v_pk_fma_f32 v[128:129], s[14:15], v[128:129], v[180:181]
	v_pk_fma_f32 v[122:123], s[14:15], v[122:123], v[182:183]
	v_pk_fma_f32 v[124:125], s[14:15], v[124:125], v[184:185]
	s_add_u32 s10, s16, 0x0
	s_addc_u32 s11, s17, 0
	global_store_dwordx4 v137, v[126:129], s[10:11] offset:0
	global_store_dwordx4 v137, v[122:125], s[10:11] offset:16
	s_add_u32 s10, s0, 0x40000
	s_addc_u32 s11, s1, 0
	global_load_dwordx4 v[140:143], v136, s[10:11]
	s_waitcnt vmcnt(9)
	v_permlane16_swap_b32_e32 v118, v114
	v_permlane16_swap_b32_e32 v119, v115
	v_permlane16_swap_b32_e32 v120, v116
	v_permlane16_swap_b32_e32 v121, v117
	v_lshlrev_b32_e32 v178, 16, v144
	v_and_b32_e32 v179, 0xffff0000, v144
	v_lshlrev_b32_e32 v180, 16, v145
	v_and_b32_e32 v181, 0xffff0000, v145
	v_lshlrev_b32_e32 v182, 16, v146
	v_and_b32_e32 v183, 0xffff0000, v146
	v_lshlrev_b32_e32 v184, 16, v147
	v_and_b32_e32 v185, 0xffff0000, v147
	v_pk_fma_f32 v[118:119], s[14:15], v[118:119], v[178:179]
	v_pk_fma_f32 v[120:121], s[14:15], v[120:121], v[180:181]
	v_pk_fma_f32 v[114:115], s[14:15], v[114:115], v[182:183]
	v_pk_fma_f32 v[116:117], s[14:15], v[116:117], v[184:185]
	s_add_u32 s10, s16, 0x0
	s_addc_u32 s11, s17, 0
	global_store_dwordx4 v137, v[118:121], s[10:11] offset:512
	global_store_dwordx4 v137, v[114:117], s[10:11] offset:528
	s_add_u32 s10, s0, 0x40000
	s_addc_u32 s11, s1, 0
	global_load_dwordx4 v[144:147], v136, s[10:11] offset:256
	s_waitcnt vmcnt(11)
	v_permlane16_swap_b32_e32 v110, v106
	v_permlane16_swap_b32_e32 v111, v107
	v_permlane16_swap_b32_e32 v112, v108
	v_permlane16_swap_b32_e32 v113, v109
	v_lshlrev_b32_e32 v178, 16, v148
	v_and_b32_e32 v179, 0xffff0000, v148
	v_lshlrev_b32_e32 v180, 16, v149
	v_and_b32_e32 v181, 0xffff0000, v149
	v_lshlrev_b32_e32 v182, 16, v150
	v_and_b32_e32 v183, 0xffff0000, v150
	v_lshlrev_b32_e32 v184, 16, v151
	v_and_b32_e32 v185, 0xffff0000, v151
	v_pk_fma_f32 v[110:111], s[14:15], v[110:111], v[178:179]
	v_pk_fma_f32 v[112:113], s[14:15], v[112:113], v[180:181]
	v_pk_fma_f32 v[106:107], s[14:15], v[106:107], v[182:183]
	v_pk_fma_f32 v[108:109], s[14:15], v[108:109], v[184:185]
	s_add_u32 s10, s16, 0x10000
	s_addc_u32 s11, s17, 0
	global_store_dwordx4 v137, v[110:113], s[10:11] offset:0
	global_store_dwordx4 v137, v[106:109], s[10:11] offset:16
	s_add_u32 s10, s0, 0x48000
	s_addc_u32 s11, s1, 0
	global_load_dwordx4 v[148:151], v136, s[10:11]
	s_waitcnt vmcnt(13)
	v_permlane16_swap_b32_e32 v102, v98
	v_permlane16_swap_b32_e32 v103, v99
	v_permlane16_swap_b32_e32 v104, v100
	v_permlane16_swap_b32_e32 v105, v101
	v_lshlrev_b32_e32 v178, 16, v152
	v_and_b32_e32 v179, 0xffff0000, v152
	v_lshlrev_b32_e32 v180, 16, v153
	v_and_b32_e32 v181, 0xffff0000, v153
	v_lshlrev_b32_e32 v182, 16, v154
	v_and_b32_e32 v183, 0xffff0000, v154
	v_lshlrev_b32_e32 v184, 16, v155
	v_and_b32_e32 v185, 0xffff0000, v155
	v_pk_fma_f32 v[102:103], s[14:15], v[102:103], v[178:179]
	v_pk_fma_f32 v[104:105], s[14:15], v[104:105], v[180:181]
	v_pk_fma_f32 v[98:99], s[14:15], v[98:99], v[182:183]
	v_pk_fma_f32 v[100:101], s[14:15], v[100:101], v[184:185]
	s_add_u32 s10, s16, 0x10000
	s_addc_u32 s11, s17, 0
	global_store_dwordx4 v137, v[102:105], s[10:11] offset:512
	global_store_dwordx4 v137, v[98:101], s[10:11] offset:528
	s_add_u32 s10, s0, 0x48000
	s_addc_u32 s11, s1, 0
	global_load_dwordx4 v[152:155], v136, s[10:11] offset:256
	s_waitcnt vmcnt(15)
	v_permlane16_swap_b32_e32 v92, v88
	v_permlane16_swap_b32_e32 v93, v89
	v_permlane16_swap_b32_e32 v94, v90
	v_permlane16_swap_b32_e32 v95, v91
	v_lshlrev_b32_e32 v178, 16, v156
	v_and_b32_e32 v179, 0xffff0000, v156
	v_lshlrev_b32_e32 v180, 16, v157
	v_and_b32_e32 v181, 0xffff0000, v157
	v_lshlrev_b32_e32 v182, 16, v158
	v_and_b32_e32 v183, 0xffff0000, v158
	v_lshlrev_b32_e32 v184, 16, v159
	v_and_b32_e32 v185, 0xffff0000, v159
	v_pk_fma_f32 v[92:93], s[14:15], v[92:93], v[178:179]
	v_pk_fma_f32 v[94:95], s[14:15], v[94:95], v[180:181]
	v_pk_fma_f32 v[88:89], s[14:15], v[88:89], v[182:183]
	v_pk_fma_f32 v[90:91], s[14:15], v[90:91], v[184:185]
	s_add_u32 s10, s16, 0x20000
	s_addc_u32 s11, s17, 0
	global_store_dwordx4 v137, v[92:95], s[10:11] offset:0
	global_store_dwordx4 v137, v[88:91], s[10:11] offset:16
	s_add_u32 s10, s0, 0x50000
	s_addc_u32 s11, s1, 0
	global_load_dwordx4 v[156:159], v136, s[10:11]
	s_waitcnt vmcnt(17)
	v_permlane16_swap_b32_e32 v84, v80
	v_permlane16_swap_b32_e32 v85, v81
	v_permlane16_swap_b32_e32 v86, v82
	v_permlane16_swap_b32_e32 v87, v83
	v_lshlrev_b32_e32 v178, 16, v160
	v_and_b32_e32 v179, 0xffff0000, v160
	v_lshlrev_b32_e32 v180, 16, v161
	v_and_b32_e32 v181, 0xffff0000, v161
	v_lshlrev_b32_e32 v182, 16, v162
	v_and_b32_e32 v183, 0xffff0000, v162
	v_lshlrev_b32_e32 v184, 16, v163
	v_and_b32_e32 v185, 0xffff0000, v163
	v_pk_fma_f32 v[84:85], s[14:15], v[84:85], v[178:179]
	v_pk_fma_f32 v[86:87], s[14:15], v[86:87], v[180:181]
	v_pk_fma_f32 v[80:81], s[14:15], v[80:81], v[182:183]
	v_pk_fma_f32 v[82:83], s[14:15], v[82:83], v[184:185]
	s_add_u32 s10, s16, 0x20000
	s_addc_u32 s11, s17, 0
	global_store_dwordx4 v137, v[84:87], s[10:11] offset:512
	global_store_dwordx4 v137, v[80:83], s[10:11] offset:528
	s_add_u32 s10, s0, 0x50000
	s_addc_u32 s11, s1, 0
	global_load_dwordx4 v[160:163], v136, s[10:11] offset:256
	s_waitcnt vmcnt(19)
	v_permlane16_swap_b32_e32 v76, v72
	v_permlane16_swap_b32_e32 v77, v73
	v_permlane16_swap_b32_e32 v78, v74
	v_permlane16_swap_b32_e32 v79, v75
	v_lshlrev_b32_e32 v178, 16, v164
	v_and_b32_e32 v179, 0xffff0000, v164
	v_lshlrev_b32_e32 v180, 16, v165
	v_and_b32_e32 v181, 0xffff0000, v165
	v_lshlrev_b32_e32 v182, 16, v166
	v_and_b32_e32 v183, 0xffff0000, v166
	v_lshlrev_b32_e32 v184, 16, v167
	v_and_b32_e32 v185, 0xffff0000, v167
	v_pk_fma_f32 v[76:77], s[14:15], v[76:77], v[178:179]
	v_pk_fma_f32 v[78:79], s[14:15], v[78:79], v[180:181]
	v_pk_fma_f32 v[72:73], s[14:15], v[72:73], v[182:183]
	v_pk_fma_f32 v[74:75], s[14:15], v[74:75], v[184:185]
	s_add_u32 s10, s16, 0x30000
	s_addc_u32 s11, s17, 0
	global_store_dwordx4 v137, v[76:79], s[10:11] offset:0
	global_store_dwordx4 v137, v[72:75], s[10:11] offset:16
	s_add_u32 s10, s0, 0x58000
	s_addc_u32 s11, s1, 0
	global_load_dwordx4 v[164:167], v136, s[10:11]
	s_waitcnt vmcnt(21)
	v_permlane16_swap_b32_e32 v68, v64
	v_permlane16_swap_b32_e32 v69, v65
	v_permlane16_swap_b32_e32 v70, v66
	v_permlane16_swap_b32_e32 v71, v67
	v_lshlrev_b32_e32 v178, 16, v174
	v_and_b32_e32 v179, 0xffff0000, v174
	v_lshlrev_b32_e32 v180, 16, v175
	v_and_b32_e32 v181, 0xffff0000, v175
	v_lshlrev_b32_e32 v182, 16, v176
	v_and_b32_e32 v183, 0xffff0000, v176
	v_lshlrev_b32_e32 v184, 16, v177
	v_and_b32_e32 v185, 0xffff0000, v177
	v_pk_fma_f32 v[68:69], s[14:15], v[68:69], v[178:179]
	v_pk_fma_f32 v[70:71], s[14:15], v[70:71], v[180:181]
	v_pk_fma_f32 v[64:65], s[14:15], v[64:65], v[182:183]
	v_pk_fma_f32 v[66:67], s[14:15], v[66:67], v[184:185]
	s_add_u32 s10, s16, 0x30000
	s_addc_u32 s11, s17, 0
	global_store_dwordx4 v137, v[68:71], s[10:11] offset:512
	global_store_dwordx4 v137, v[64:67], s[10:11] offset:528
	s_add_u32 s10, s0, 0x58000
	s_addc_u32 s11, s1, 0
	global_load_dwordx4 v[174:177], v136, s[10:11] offset:256
	s_waitcnt vmcnt(21)
	v_permlane16_swap_b32_e32 v60, v56
	v_permlane16_swap_b32_e32 v61, v57
	v_permlane16_swap_b32_e32 v62, v58
	v_permlane16_swap_b32_e32 v63, v59
	v_lshlrev_b32_e32 v178, 16, v140
	v_and_b32_e32 v179, 0xffff0000, v140
	v_lshlrev_b32_e32 v180, 16, v141
	v_and_b32_e32 v181, 0xffff0000, v141
	v_lshlrev_b32_e32 v182, 16, v142
	v_and_b32_e32 v183, 0xffff0000, v142
	v_lshlrev_b32_e32 v184, 16, v143
	v_and_b32_e32 v185, 0xffff0000, v143
	v_pk_fma_f32 v[60:61], s[14:15], v[60:61], v[178:179]
	v_pk_fma_f32 v[62:63], s[14:15], v[62:63], v[180:181]
	v_pk_fma_f32 v[56:57], s[14:15], v[56:57], v[182:183]
	v_pk_fma_f32 v[58:59], s[14:15], v[58:59], v[184:185]
	s_add_u32 s10, s16, 0x80000
	s_addc_u32 s11, s17, 0
	global_store_dwordx4 v137, v[60:63], s[10:11] offset:0
	global_store_dwordx4 v137, v[56:59], s[10:11] offset:16
	s_waitcnt vmcnt(20)
	v_permlane16_swap_b32_e32 v52, v48
	v_permlane16_swap_b32_e32 v53, v49
	v_permlane16_swap_b32_e32 v54, v50
	v_permlane16_swap_b32_e32 v55, v51
	v_lshlrev_b32_e32 v178, 16, v144
	v_and_b32_e32 v179, 0xffff0000, v144
	v_lshlrev_b32_e32 v180, 16, v145
	v_and_b32_e32 v181, 0xffff0000, v145
	v_lshlrev_b32_e32 v182, 16, v146
	v_and_b32_e32 v183, 0xffff0000, v146
	v_lshlrev_b32_e32 v184, 16, v147
	v_and_b32_e32 v185, 0xffff0000, v147
	v_pk_fma_f32 v[52:53], s[14:15], v[52:53], v[178:179]
	v_pk_fma_f32 v[54:55], s[14:15], v[54:55], v[180:181]
	v_pk_fma_f32 v[48:49], s[14:15], v[48:49], v[182:183]
	v_pk_fma_f32 v[50:51], s[14:15], v[50:51], v[184:185]
	s_add_u32 s10, s16, 0x80000
	s_addc_u32 s11, s17, 0
	global_store_dwordx4 v137, v[52:55], s[10:11] offset:512
	global_store_dwordx4 v137, v[48:51], s[10:11] offset:528
	s_waitcnt vmcnt(19)
	v_permlane16_swap_b32_e32 v44, v40
	v_permlane16_swap_b32_e32 v45, v41
	v_permlane16_swap_b32_e32 v46, v42
	v_permlane16_swap_b32_e32 v47, v43
	v_lshlrev_b32_e32 v178, 16, v148
	v_and_b32_e32 v179, 0xffff0000, v148
	v_lshlrev_b32_e32 v180, 16, v149
	v_and_b32_e32 v181, 0xffff0000, v149
	v_lshlrev_b32_e32 v182, 16, v150
	v_and_b32_e32 v183, 0xffff0000, v150
	v_lshlrev_b32_e32 v184, 16, v151
	v_and_b32_e32 v185, 0xffff0000, v151
	v_pk_fma_f32 v[44:45], s[14:15], v[44:45], v[178:179]
	v_pk_fma_f32 v[46:47], s[14:15], v[46:47], v[180:181]
	v_pk_fma_f32 v[40:41], s[14:15], v[40:41], v[182:183]
	v_pk_fma_f32 v[42:43], s[14:15], v[42:43], v[184:185]
	s_add_u32 s10, s16, 0x90000
	s_addc_u32 s11, s17, 0
	global_store_dwordx4 v137, v[44:47], s[10:11] offset:0
	global_store_dwordx4 v137, v[40:43], s[10:11] offset:16
	s_waitcnt vmcnt(18)
	v_permlane16_swap_b32_e32 v36, v32
	v_permlane16_swap_b32_e32 v37, v33
	v_permlane16_swap_b32_e32 v38, v34
	v_permlane16_swap_b32_e32 v39, v35
	v_lshlrev_b32_e32 v178, 16, v152
	v_and_b32_e32 v179, 0xffff0000, v152
	v_lshlrev_b32_e32 v180, 16, v153
	v_and_b32_e32 v181, 0xffff0000, v153
	v_lshlrev_b32_e32 v182, 16, v154
	v_and_b32_e32 v183, 0xffff0000, v154
	v_lshlrev_b32_e32 v184, 16, v155
	v_and_b32_e32 v185, 0xffff0000, v155
	v_pk_fma_f32 v[36:37], s[14:15], v[36:37], v[178:179]
	v_pk_fma_f32 v[38:39], s[14:15], v[38:39], v[180:181]
	v_pk_fma_f32 v[32:33], s[14:15], v[32:33], v[182:183]
	v_pk_fma_f32 v[34:35], s[14:15], v[34:35], v[184:185]
	s_add_u32 s10, s16, 0x90000
	s_addc_u32 s11, s17, 0
	global_store_dwordx4 v137, v[36:39], s[10:11] offset:512
	global_store_dwordx4 v137, v[32:35], s[10:11] offset:528
	s_waitcnt vmcnt(17)
	v_permlane16_swap_b32_e32 v28, v24
	v_permlane16_swap_b32_e32 v29, v25
	v_permlane16_swap_b32_e32 v30, v26
	v_permlane16_swap_b32_e32 v31, v27
	v_lshlrev_b32_e32 v178, 16, v156
	v_and_b32_e32 v179, 0xffff0000, v156
	v_lshlrev_b32_e32 v180, 16, v157
	v_and_b32_e32 v181, 0xffff0000, v157
	v_lshlrev_b32_e32 v182, 16, v158
	v_and_b32_e32 v183, 0xffff0000, v158
	v_lshlrev_b32_e32 v184, 16, v159
	v_and_b32_e32 v185, 0xffff0000, v159
	v_pk_fma_f32 v[28:29], s[14:15], v[28:29], v[178:179]
	v_pk_fma_f32 v[30:31], s[14:15], v[30:31], v[180:181]
	v_pk_fma_f32 v[24:25], s[14:15], v[24:25], v[182:183]
	v_pk_fma_f32 v[26:27], s[14:15], v[26:27], v[184:185]
	s_add_u32 s10, s16, 0xa0000
	s_addc_u32 s11, s17, 0
	global_store_dwordx4 v137, v[28:31], s[10:11] offset:0
	global_store_dwordx4 v137, v[24:27], s[10:11] offset:16
	s_waitcnt vmcnt(16)
	v_permlane16_swap_b32_e32 v20, v16
	v_permlane16_swap_b32_e32 v21, v17
	v_permlane16_swap_b32_e32 v22, v18
	v_permlane16_swap_b32_e32 v23, v19
	v_lshlrev_b32_e32 v178, 16, v160
	v_and_b32_e32 v179, 0xffff0000, v160
	v_lshlrev_b32_e32 v180, 16, v161
	v_and_b32_e32 v181, 0xffff0000, v161
	v_lshlrev_b32_e32 v182, 16, v162
	v_and_b32_e32 v183, 0xffff0000, v162
	v_lshlrev_b32_e32 v184, 16, v163
	v_and_b32_e32 v185, 0xffff0000, v163
	v_pk_fma_f32 v[20:21], s[14:15], v[20:21], v[178:179]
	v_pk_fma_f32 v[22:23], s[14:15], v[22:23], v[180:181]
	v_pk_fma_f32 v[16:17], s[14:15], v[16:17], v[182:183]
	v_pk_fma_f32 v[18:19], s[14:15], v[18:19], v[184:185]
	s_add_u32 s10, s16, 0xa0000
	s_addc_u32 s11, s17, 0
	global_store_dwordx4 v137, v[20:23], s[10:11] offset:512
	global_store_dwordx4 v137, v[16:19], s[10:11] offset:528
	s_waitcnt vmcnt(15)
	v_permlane16_swap_b32_e32 v12, v8
	v_permlane16_swap_b32_e32 v13, v9
	v_permlane16_swap_b32_e32 v14, v10
	v_permlane16_swap_b32_e32 v15, v11
	v_lshlrev_b32_e32 v178, 16, v164
	v_and_b32_e32 v179, 0xffff0000, v164
	v_lshlrev_b32_e32 v180, 16, v165
	v_and_b32_e32 v181, 0xffff0000, v165
	v_lshlrev_b32_e32 v182, 16, v166
	v_and_b32_e32 v183, 0xffff0000, v166
	v_lshlrev_b32_e32 v184, 16, v167
	v_and_b32_e32 v185, 0xffff0000, v167
	v_pk_fma_f32 v[12:13], s[14:15], v[12:13], v[178:179]
	v_pk_fma_f32 v[14:15], s[14:15], v[14:15], v[180:181]
	v_pk_fma_f32 v[8:9], s[14:15], v[8:9], v[182:183]
	v_pk_fma_f32 v[10:11], s[14:15], v[10:11], v[184:185]
	s_add_u32 s10, s16, 0xb0000
	s_addc_u32 s11, s17, 0
	global_store_dwordx4 v137, v[12:15], s[10:11] offset:0
	global_store_dwordx4 v137, v[8:11], s[10:11] offset:16
	s_waitcnt vmcnt(14)
	v_permlane16_swap_b32_e32 v4, v0
	v_permlane16_swap_b32_e32 v5, v1
	v_permlane16_swap_b32_e32 v6, v2
	v_permlane16_swap_b32_e32 v7, v3
	v_lshlrev_b32_e32 v178, 16, v174
	v_and_b32_e32 v179, 0xffff0000, v174
	v_lshlrev_b32_e32 v180, 16, v175
	v_and_b32_e32 v181, 0xffff0000, v175
	v_lshlrev_b32_e32 v182, 16, v176
	v_and_b32_e32 v183, 0xffff0000, v176
	v_lshlrev_b32_e32 v184, 16, v177
	v_and_b32_e32 v185, 0xffff0000, v177
	v_pk_fma_f32 v[4:5], s[14:15], v[4:5], v[178:179]
	v_pk_fma_f32 v[6:7], s[14:15], v[6:7], v[180:181]
	v_pk_fma_f32 v[0:1], s[14:15], v[0:1], v[182:183]
	v_pk_fma_f32 v[2:3], s[14:15], v[2:3], v[184:185]
	s_add_u32 s10, s16, 0xb0000
	s_addc_u32 s11, s17, 0
	global_store_dwordx4 v137, v[4:7], s[10:11] offset:512
	global_store_dwordx4 v137, v[0:3], s[10:11] offset:528
	s_mov_b32 s101, 1

.LBB0_1131:
	s_add_u32 s20, s2, 0xfffc0080
	s_addc_u32 s21, s3, -1
	s_add_i32 s44, 0, 0x10000
	s_cmp_eq_u32 s43, 12
	s_cselect_b32 s23, s15, s21
	s_cselect_b32 s22, s39, s20
	v_add_u32_e32 v173, s44, v169
	s_cselect_b32 s21, s13, s42
	s_cselect_b32 s20, s40, s41
	s_add_i32 s46, 0, 0x14000
	ds_read_b128 v[130:133], v173
	ds_read_b128 v[134:137], v173 offset:1024
	ds_read_b128 v[138:141], v173 offset:2048
	ds_read_b128 v[178:181], v173 offset:3072
	v_add_u32_e32 v173, s46, v169
	ds_read_b128 v[182:185], v173
	ds_read_b128 v[186:189], v173 offset:1024
	ds_read_b128 v[190:193], v173 offset:2048
	ds_read_b128 v[194:197], v173 offset:3072
	v_lshl_add_u64 v[246:247], s[2:3], 0, v[174:175]
	s_add_i32 m0, s29, 0xc000
	ds_read_b128 v[198:201], v149
	ds_read_b128 v[202:205], v149 offset:1024
	ds_read_b128 v[222:225], v149 offset:2048
	ds_read_b128 v[226:229], v149 offset:3072
	ds_read_b128 v[230:233], v149 offset:4096
	ds_read_b128 v[234:237], v149 offset:5120
	ds_read_b128 v[238:241], v149 offset:6144
	ds_read_b128 v[242:245], v149 offset:7168
	global_load_lds_dwordx4 v[246:247], off
	v_lshl_add_u64 v[246:247], s[2:3], 0, v[176:177]
	s_add_i32 m0, s29, 0xe000
	s_nop 0
	global_load_lds_dwordx4 v[246:247], off
	s_cmp_eq_u32 s101, 1
	s_cbranch_scc1 .Lfw_3
	s_waitcnt vmcnt(8)
.Lfw_3:
	s_waitcnt lgkmcnt(0)
	s_barrier
	s_setprio 1
	s_waitcnt lgkmcnt(0)
	v_mfma_f32_16x16x32_bf16 v[118:121], v[130:133], v[198:201], v[118:121]
	v_mfma_f32_16x16x32_bf16 v[114:117], v[138:141], v[198:201], v[114:117]
	v_mfma_f32_16x16x32_bf16 v[110:113], v[130:133], v[222:225], v[110:113]
	v_mfma_f32_16x16x32_bf16 v[102:105], v[138:141], v[222:225], v[102:105]
	v_mfma_f32_16x16x32_bf16 v[92:95], v[130:133], v[230:233], v[92:95]
	v_mfma_f32_16x16x32_bf16 v[84:87], v[138:141], v[230:233], v[84:87]
	v_mfma_f32_16x16x32_bf16 v[76:79], v[130:133], v[238:241], v[76:79]
	v_mfma_f32_16x16x32_bf16 v[68:71], v[138:141], v[238:241], v[68:71]
	v_mfma_f32_16x16x32_bf16 v[118:121], v[134:137], v[202:205], v[118:121]
	v_mfma_f32_16x16x32_bf16 v[114:117], v[178:181], v[202:205], v[114:117]
	v_mfma_f32_16x16x32_bf16 v[110:113], v[134:137], v[226:229], v[110:113]
	v_mfma_f32_16x16x32_bf16 v[102:105], v[178:181], v[226:229], v[102:105]
	v_mfma_f32_16x16x32_bf16 v[92:95], v[134:137], v[234:237], v[92:95]
	v_mfma_f32_16x16x32_bf16 v[84:87], v[178:181], v[234:237], v[84:87]
	v_mfma_f32_16x16x32_bf16 v[76:79], v[134:137], v[242:245], v[76:79]
	v_mfma_f32_16x16x32_bf16 v[68:71], v[178:181], v[242:245], v[68:71]
	s_setprio 0
	s_setprio 1
	v_mfma_f32_16x16x32_bf16 v[126:129], v[182:185], v[198:201], v[126:129]
	v_mfma_f32_16x16x32_bf16 v[122:125], v[190:193], v[198:201], v[122:125]
	v_mfma_f32_16x16x32_bf16 v[106:109], v[182:185], v[222:225], v[106:109]
	v_mfma_f32_16x16x32_bf16 v[98:101], v[190:193], v[222:225], v[98:101]
	v_mfma_f32_16x16x32_bf16 v[88:91], v[182:185], v[230:233], v[88:91]
	v_mfma_f32_16x16x32_bf16 v[80:83], v[190:193], v[230:233], v[80:83]
	v_mfma_f32_16x16x32_bf16 v[72:75], v[182:185], v[238:241], v[72:75]
	v_mfma_f32_16x16x32_bf16 v[64:67], v[190:193], v[238:241], v[64:67]
	v_mfma_f32_16x16x32_bf16 v[126:129], v[186:189], v[202:205], v[126:129]
	v_mfma_f32_16x16x32_bf16 v[122:125], v[194:197], v[202:205], v[122:125]
	v_mfma_f32_16x16x32_bf16 v[106:109], v[186:189], v[226:229], v[106:109]
	v_mfma_f32_16x16x32_bf16 v[98:101], v[194:197], v[226:229], v[98:101]
	v_mfma_f32_16x16x32_bf16 v[88:91], v[186:189], v[234:237], v[88:91]
	v_mfma_f32_16x16x32_bf16 v[80:83], v[194:197], v[234:237], v[80:83]
	v_mfma_f32_16x16x32_bf16 v[72:75], v[186:189], v[242:245], v[72:75]
	v_mfma_f32_16x16x32_bf16 v[64:67], v[194:197], v[242:245], v[64:67]
	s_setprio 0
	s_barrier
	s_add_i32 s44, s44, s27
	v_lshl_add_u64 v[246:247], s[20:21], 0, v[96:97]
	s_mov_b32 m0, s44
	ds_read_b128 v[198:201], v149 offset:16384
	ds_read_b128 v[202:205], v149 offset:17408
	ds_read_b128 v[222:225], v149 offset:18432
	ds_read_b128 v[226:229], v149 offset:19456
	ds_read_b128 v[230:233], v149 offset:20480
	ds_read_b128 v[234:237], v149 offset:21504
	ds_read_b128 v[238:241], v149 offset:22528
	ds_read_b128 v[242:245], v149 offset:23552
	global_load_lds_dwordx4 v[246:247], off
	s_add_i32 m0, s44, 0x2000
	s_add_u32 s44, s20, 0x40000
	v_lshl_add_u64 v[248:249], s[20:21], 0, v[142:143]
	s_addc_u32 s45, s21, 0
	s_add_i32 s46, s46, s27
	global_load_lds_dwordx4 v[248:249], off
	v_lshl_add_u64 v[220:221], s[44:45], 0, v[96:97]
	s_mov_b32 m0, s46
	v_lshl_add_u64 v[212:213], s[22:23], 0, v[144:145]
	global_load_lds_dwordx4 v[220:221], off
	v_lshl_add_u64 v[220:221], s[44:45], 0, v[142:143]
	s_add_i32 m0, s46, 0x2000
	s_nop 0
	global_load_lds_dwordx4 v[220:221], off
	v_lshl_add_u64 v[220:221], s[22:23], 0, v[146:147]
	s_mov_b32 m0, s29
	s_nop 0
	global_load_lds_dwordx4 v[220:221], off
	s_mov_b32 m0, s30
	s_nop 0
	global_load_lds_dwordx4 v[212:213], off
	s_cmp_eq_u32 s101, 1
	s_cbranch_scc1 .Lfw_4
	s_waitcnt vmcnt(8)
.Lfw_4:
	s_waitcnt lgkmcnt(0)
	s_barrier
	s_setprio 1
	s_waitcnt lgkmcnt(0)
	v_mfma_f32_16x16x32_bf16 v[60:63], v[130:133], v[198:201], v[60:63]
	v_mfma_f32_16x16x32_bf16 v[52:55], v[138:141], v[198:201], v[52:55]
	v_mfma_f32_16x16x32_bf16 v[44:47], v[130:133], v[222:225], v[44:47]
	v_mfma_f32_16x16x32_bf16 v[36:39], v[138:141], v[222:225], v[36:39]
	v_mfma_f32_16x16x32_bf16 v[28:31], v[130:133], v[230:233], v[28:31]
	v_mfma_f32_16x16x32_bf16 v[20:23], v[138:141], v[230:233], v[20:23]
	v_mfma_f32_16x16x32_bf16 v[12:15], v[130:133], v[238:241], v[12:15]
	v_mfma_f32_16x16x32_bf16 v[4:7], v[138:141], v[238:241], v[4:7]
	v_mfma_f32_16x16x32_bf16 v[60:63], v[134:137], v[202:205], v[60:63]
	v_mfma_f32_16x16x32_bf16 v[52:55], v[178:181], v[202:205], v[52:55]
	v_mfma_f32_16x16x32_bf16 v[44:47], v[134:137], v[226:229], v[44:47]
	v_mfma_f32_16x16x32_bf16 v[36:39], v[178:181], v[226:229], v[36:39]
	v_mfma_f32_16x16x32_bf16 v[28:31], v[134:137], v[234:237], v[28:31]
	v_mfma_f32_16x16x32_bf16 v[20:23], v[178:181], v[234:237], v[20:23]
	v_mfma_f32_16x16x32_bf16 v[12:15], v[134:137], v[242:245], v[12:15]
	v_mfma_f32_16x16x32_bf16 v[4:7], v[178:181], v[242:245], v[4:7]
	s_setprio 0
	s_setprio 1
	v_mfma_f32_16x16x32_bf16 v[56:59], v[182:185], v[198:201], v[56:59]
	v_mfma_f32_16x16x32_bf16 v[48:51], v[190:193], v[198:201], v[48:51]
	v_mfma_f32_16x16x32_bf16 v[40:43], v[182:185], v[222:225], v[40:43]
	v_mfma_f32_16x16x32_bf16 v[32:35], v[190:193], v[222:225], v[32:35]
	v_mfma_f32_16x16x32_bf16 v[24:27], v[182:185], v[230:233], v[24:27]
	v_mfma_f32_16x16x32_bf16 v[16:19], v[190:193], v[230:233], v[16:19]
	v_mfma_f32_16x16x32_bf16 v[8:11], v[182:185], v[238:241], v[8:11]
	v_mfma_f32_16x16x32_bf16 v[0:3], v[190:193], v[238:241], v[0:3]
	v_mfma_f32_16x16x32_bf16 v[56:59], v[186:189], v[202:205], v[56:59]
	v_mfma_f32_16x16x32_bf16 v[48:51], v[194:197], v[202:205], v[48:51]
	v_mfma_f32_16x16x32_bf16 v[40:43], v[186:189], v[226:229], v[40:43]
	v_mfma_f32_16x16x32_bf16 v[32:35], v[194:197], v[226:229], v[32:35]
	v_mfma_f32_16x16x32_bf16 v[24:27], v[186:189], v[234:237], v[24:27]
	v_mfma_f32_16x16x32_bf16 v[16:19], v[194:197], v[234:237], v[16:19]
	v_mfma_f32_16x16x32_bf16 v[8:11], v[186:189], v[242:245], v[8:11]
	v_mfma_f32_16x16x32_bf16 v[0:3], v[194:197], v[242:245], v[0:3]
	s_setprio 0
	s_barrier
	s_add_i32 s44, 0, 0x18000
	v_add_u32_e32 v173, s44, v169
	s_add_i32 s45, 0, 0x1c000
	ds_read_b128 v[130:133], v173
	ds_read_b128 v[134:137], v173 offset:1024
	ds_read_b128 v[138:141], v173 offset:2048
	ds_read_b128 v[178:181], v173 offset:3072
	v_add_u32_e32 v173, s45, v169
	ds_read_b128 v[182:185], v173
	ds_read_b128 v[186:189], v173 offset:1024
	ds_read_b128 v[190:193], v173 offset:2048
	ds_read_b128 v[194:197], v173 offset:3072
	s_add_u32 s22, s22, 0x40000
	s_addc_u32 s23, s23, 0
	s_mov_b32 m0, s31
	v_lshl_add_u64 v[214:215], s[22:23], 0, v[146:147]
	ds_read_b128 v[198:201], v149 offset:32768
	ds_read_b128 v[202:205], v149 offset:33792
	ds_read_b128 v[222:225], v149 offset:34816
	ds_read_b128 v[226:229], v149 offset:35840
	ds_read_b128 v[230:233], v149 offset:36864
	ds_read_b128 v[234:237], v149 offset:37888
	ds_read_b128 v[238:241], v149 offset:38912
	ds_read_b128 v[242:245], v149 offset:39936
	global_load_lds_dwordx4 v[214:215], off
	v_lshl_add_u64 v[214:215], s[22:23], 0, v[144:145]
	s_mov_b32 m0, s33
	s_nop 0
	global_load_lds_dwordx4 v[214:215], off
	s_waitcnt vmcnt(8)
	s_waitcnt lgkmcnt(0)
	s_barrier
	s_setprio 1
	s_waitcnt lgkmcnt(0)
	v_mfma_f32_16x16x32_bf16 v[118:121], v[130:133], v[198:201], v[118:121]
	v_mfma_f32_16x16x32_bf16 v[114:117], v[138:141], v[198:201], v[114:117]
	v_mfma_f32_16x16x32_bf16 v[110:113], v[130:133], v[222:225], v[110:113]
	v_mfma_f32_16x16x32_bf16 v[102:105], v[138:141], v[222:225], v[102:105]
	v_mfma_f32_16x16x32_bf16 v[92:95], v[130:133], v[230:233], v[92:95]
	v_mfma_f32_16x16x32_bf16 v[84:87], v[138:141], v[230:233], v[84:87]
	v_mfma_f32_16x16x32_bf16 v[76:79], v[130:133], v[238:241], v[76:79]
	v_mfma_f32_16x16x32_bf16 v[68:71], v[138:141], v[238:241], v[68:71]
	v_mfma_f32_16x16x32_bf16 v[118:121], v[134:137], v[202:205], v[118:121]
	v_mfma_f32_16x16x32_bf16 v[114:117], v[178:181], v[202:205], v[114:117]
	v_mfma_f32_16x16x32_bf16 v[110:113], v[134:137], v[226:229], v[110:113]
	v_mfma_f32_16x16x32_bf16 v[102:105], v[178:181], v[226:229], v[102:105]
	v_mfma_f32_16x16x32_bf16 v[92:95], v[134:137], v[234:237], v[92:95]
	v_mfma_f32_16x16x32_bf16 v[84:87], v[178:181], v[234:237], v[84:87]
	v_mfma_f32_16x16x32_bf16 v[76:79], v[134:137], v[242:245], v[76:79]
	v_mfma_f32_16x16x32_bf16 v[68:71], v[178:181], v[242:245], v[68:71]
	s_setprio 0
	s_setprio 1
	v_mfma_f32_16x16x32_bf16 v[126:129], v[182:185], v[198:201], v[126:129]
	v_mfma_f32_16x16x32_bf16 v[122:125], v[190:193], v[198:201], v[122:125]
	v_mfma_f32_16x16x32_bf16 v[106:109], v[182:185], v[222:225], v[106:109]
	v_mfma_f32_16x16x32_bf16 v[98:101], v[190:193], v[222:225], v[98:101]
	v_mfma_f32_16x16x32_bf16 v[88:91], v[182:185], v[230:233], v[88:91]
	v_mfma_f32_16x16x32_bf16 v[80:83], v[190:193], v[230:233], v[80:83]
	v_mfma_f32_16x16x32_bf16 v[72:75], v[182:185], v[238:241], v[72:75]
	v_mfma_f32_16x16x32_bf16 v[64:67], v[190:193], v[238:241], v[64:67]
	v_mfma_f32_16x16x32_bf16 v[126:129], v[186:189], v[202:205], v[126:129]
	v_mfma_f32_16x16x32_bf16 v[122:125], v[194:197], v[202:205], v[122:125]
	v_mfma_f32_16x16x32_bf16 v[106:109], v[186:189], v[226:229], v[106:109]
	v_mfma_f32_16x16x32_bf16 v[98:101], v[194:197], v[226:229], v[98:101]
	v_mfma_f32_16x16x32_bf16 v[88:91], v[186:189], v[234:237], v[88:91]
	v_mfma_f32_16x16x32_bf16 v[80:83], v[194:197], v[234:237], v[80:83]
	v_mfma_f32_16x16x32_bf16 v[72:75], v[186:189], v[242:245], v[72:75]
	v_mfma_f32_16x16x32_bf16 v[64:67], v[194:197], v[242:245], v[64:67]
	s_setprio 0
	s_barrier
	s_add_i32 s22, s44, s27
	v_lshl_add_u64 v[214:215], v[246:247], 0, s[90:91]
	s_mov_b32 m0, s22
	ds_read_b128 v[198:201], v149 offset:49152
	ds_read_b128 v[202:205], v149 offset:50176
	ds_read_b128 v[222:225], v149 offset:51200
	ds_read_b128 v[226:229], v149 offset:52224
	ds_read_b128 v[230:233], v149 offset:53248
	ds_read_b128 v[234:237], v149 offset:54272
	ds_read_b128 v[238:241], v149 offset:55296
	ds_read_b128 v[242:245], v149 offset:56320
	global_load_lds_dwordx4 v[214:215], off
	s_add_i32 m0, s22, 0x2000
	s_add_u32 s20, s20, 0x40080
	v_lshl_add_u64 v[214:215], v[248:249], 0, s[90:91]
	s_addc_u32 s21, s21, 0
	s_add_i32 s22, s45, s27
	global_load_lds_dwordx4 v[214:215], off
	v_lshl_add_u64 v[214:215], s[20:21], 0, v[96:97]
	s_mov_b32 m0, s22
	v_lshl_add_u64 v[212:213], v[212:213], 0, s[90:91]
	global_load_lds_dwordx4 v[214:215], off
	v_lshl_add_u64 v[214:215], s[20:21], 0, v[142:143]
	s_add_i32 m0, s22, 0x2000
	s_nop 0
	global_load_lds_dwordx4 v[214:215], off
	v_lshl_add_u64 v[214:215], v[220:221], 0, s[90:91]
	s_mov_b32 m0, s34
	s_nop 0
	global_load_lds_dwordx4 v[214:215], off
	s_mov_b32 m0, s35
	s_nop 0
	global_load_lds_dwordx4 v[212:213], off
	s_waitcnt vmcnt(8)
	s_waitcnt lgkmcnt(0)
	s_barrier
	s_setprio 1
	s_waitcnt lgkmcnt(0)
	v_mfma_f32_16x16x32_bf16 v[60:63], v[130:133], v[198:201], v[60:63]
	v_mfma_f32_16x16x32_bf16 v[52:55], v[138:141], v[198:201], v[52:55]
	v_mfma_f32_16x16x32_bf16 v[44:47], v[130:133], v[222:225], v[44:47]
	v_mfma_f32_16x16x32_bf16 v[36:39], v[138:141], v[222:225], v[36:39]
	v_mfma_f32_16x16x32_bf16 v[28:31], v[130:133], v[230:233], v[28:31]
	v_mfma_f32_16x16x32_bf16 v[20:23], v[138:141], v[230:233], v[20:23]
	v_mfma_f32_16x16x32_bf16 v[12:15], v[130:133], v[238:241], v[12:15]
	v_mfma_f32_16x16x32_bf16 v[4:7], v[138:141], v[238:241], v[4:7]
	v_mfma_f32_16x16x32_bf16 v[60:63], v[134:137], v[202:205], v[60:63]
	v_mfma_f32_16x16x32_bf16 v[52:55], v[178:181], v[202:205], v[52:55]
	v_mfma_f32_16x16x32_bf16 v[44:47], v[134:137], v[226:229], v[44:47]
	v_mfma_f32_16x16x32_bf16 v[36:39], v[178:181], v[226:229], v[36:39]
	v_mfma_f32_16x16x32_bf16 v[28:31], v[134:137], v[234:237], v[28:31]
	v_mfma_f32_16x16x32_bf16 v[20:23], v[178:181], v[234:237], v[20:23]
	v_mfma_f32_16x16x32_bf16 v[12:15], v[134:137], v[242:245], v[12:15]
	v_mfma_f32_16x16x32_bf16 v[4:7], v[178:181], v[242:245], v[4:7]
	s_setprio 0
	s_setprio 1
	v_mfma_f32_16x16x32_bf16 v[56:59], v[182:185], v[198:201], v[56:59]
	v_mfma_f32_16x16x32_bf16 v[48:51], v[190:193], v[198:201], v[48:51]
	v_mfma_f32_16x16x32_bf16 v[40:43], v[182:185], v[222:225], v[40:43]
	v_mfma_f32_16x16x32_bf16 v[32:35], v[190:193], v[222:225], v[32:35]
	v_mfma_f32_16x16x32_bf16 v[24:27], v[182:185], v[230:233], v[24:27]
	v_mfma_f32_16x16x32_bf16 v[16:19], v[190:193], v[230:233], v[16:19]
	v_mfma_f32_16x16x32_bf16 v[8:11], v[182:185], v[238:241], v[8:11]
	v_mfma_f32_16x16x32_bf16 v[0:3], v[190:193], v[238:241], v[0:3]
	v_mfma_f32_16x16x32_bf16 v[56:59], v[186:189], v[202:205], v[56:59]
	v_mfma_f32_16x16x32_bf16 v[48:51], v[194:197], v[202:205], v[48:51]
	v_mfma_f32_16x16x32_bf16 v[40:43], v[186:189], v[226:229], v[40:43]
	v_mfma_f32_16x16x32_bf16 v[32:35], v[194:197], v[226:229], v[32:35]
	v_mfma_f32_16x16x32_bf16 v[24:27], v[186:189], v[234:237], v[24:27]
	v_mfma_f32_16x16x32_bf16 v[16:19], v[194:197], v[234:237], v[16:19]
	v_mfma_f32_16x16x32_bf16 v[8:11], v[186:189], v[242:245], v[8:11]
	v_mfma_f32_16x16x32_bf16 v[0:3], v[194:197], v[242:245], v[0:3]
	s_setprio 0
	s_barrier
	s_mov_b32 s101, 0
	s_add_i32 s43, s43, 2
	s_add_u32 s2, s2, 0x100
	s_addc_u32 s3, s3, 0
	s_add_u32 s41, s41, 0x100
	s_addc_u32 s42, s42, 0
	s_cmp_gt_u32 s43, 13
	s_cbranch_scc0 .LBB0_1131
	s_and_b64 vcc, exec, s[10:11]
	s_cbranch_vccz .LBB0_1134
	s_barrier
.LBB0_1134:
	v_lshl_add_u32 v130, s0, 8, v148
	v_ashrrev_i32_e32 v131, 31, v130
	v_lshl_add_u64 v[190:191], v[130:131], 4, s[8:9]
	global_load_dwordx4 v[222:225], v[190:191], off
	global_load_dwordx4 v[226:229], v[190:191], off offset:256
	global_load_dwordx4 v[230:233], v[190:191], off offset:512
	global_load_dwordx4 v[234:237], v[190:191], off offset:768
	global_load_dwordx4 v[238:241], v[190:191], off offset:2048
	global_load_dwordx4 v[242:245], v[190:191], off offset:2304
	global_load_dwordx4 v[198:201], v[190:191], off offset:2560
	global_load_dwordx4 v[202:205], v[190:191], off offset:2816
	s_lshl_b32 s1, s1, 1
	s_or_b32 s1, s1, s36
	s_mul_hi_i32 s2, s0, 44
	s_mul_i32 s0, s0, 44
	s_ashr_i32 s3, s1, 31
	s_add_u32 s0, s0, s1
	s_addc_u32 s1, s2, s3
	s_lshl_b64 s[0:1], s[0:1], 15
	v_lshl_add_u64 v[178:179], v[166:167], 0, s[0:1]
	v_lshl_add_u64 v[178:179], v[178:179], 0, v[150:151]
	s_mov_b64 s[2:3], 0x1000
	v_lshl_add_u64 v[180:181], v[178:179], 0, s[2:3]
	s_mov_b64 s[2:3], 0x5000
	v_lshl_add_u64 v[182:183], v[178:179], 0, s[2:3]
	s_mov_b32 s2, 0xbfb8aa3b
	s_mov_b32 s3, 0xbfb8aa3b
	s_mov_b32 s100, 1.0
	s_mov_b32 s101, 1.0
	s_waitcnt vmcnt(7)
	v_add_f32_e32 v140, v222, v223
	v_add_f32_e32 v141, v224, v225
	v_add_f32_e32 v140, v140, v141
	v_fmamk_f32 v140, v140, 0x3a800000, v207
	v_rsq_f32_e32 v184, v140
	s_nop 0
	v_pk_mul_f32 v[118:119], v[118:119], v[184:185] op_sel_hi:[1,0]
	v_pk_mul_f32 v[120:121], v[120:121], v[184:185] op_sel_hi:[1,0]
	v_pk_mul_f32 v[114:115], v[114:115], v[184:185] op_sel_hi:[1,0]
	v_pk_mul_f32 v[116:117], v[116:117], v[184:185] op_sel_hi:[1,0]
	v_pk_mul_f32 v[126:127], v[126:127], v[184:185] op_sel_hi:[1,0]
	v_pk_mul_f32 v[128:129], v[128:129], v[184:185] op_sel_hi:[1,0]
	v_pk_mul_f32 v[122:123], v[122:123], v[184:185] op_sel_hi:[1,0]
	v_pk_mul_f32 v[124:125], v[124:125], v[184:185] op_sel_hi:[1,0]
	v_pk_mul_f32 v[132:133], v[118:119], s[2:3]
	v_pk_mul_f32 v[134:135], v[120:121], s[2:3]
	v_pk_mul_f32 v[136:137], v[114:115], s[2:3]
	v_pk_mul_f32 v[138:139], v[116:117], s[2:3]
	v_exp_f32_e32 v132, v132
	v_exp_f32_e32 v133, v133
	v_exp_f32_e32 v134, v134
	v_exp_f32_e32 v135, v135
	v_exp_f32_e32 v136, v136
	v_exp_f32_e32 v137, v137
	v_exp_f32_e32 v138, v138
	v_exp_f32_e32 v139, v139
	v_pk_add_f32 v[132:133], v[132:133], s[100:101]
	v_pk_add_f32 v[134:135], v[134:135], s[100:101]
	v_pk_add_f32 v[136:137], v[136:137], s[100:101]
	v_pk_add_f32 v[138:139], v[138:139], s[100:101]
	v_rcp_f32_e32 v132, v132
	v_rcp_f32_e32 v133, v133
	v_rcp_f32_e32 v134, v134
	v_rcp_f32_e32 v135, v135
	v_rcp_f32_e32 v136, v136
	v_rcp_f32_e32 v137, v137
	v_rcp_f32_e32 v138, v138
	v_rcp_f32_e32 v139, v139
	v_pk_mul_f32 v[118:119], v[118:119], v[132:133]
	v_pk_mul_f32 v[120:121], v[120:121], v[134:135]
	v_pk_mul_f32 v[114:115], v[114:115], v[136:137]
	v_pk_mul_f32 v[116:117], v[116:117], v[138:139]
	v_pk_mul_f32 v[118:119], v[118:119], v[126:127]
	v_pk_mul_f32 v[120:121], v[120:121], v[128:129]
	v_pk_mul_f32 v[114:115], v[114:115], v[122:123]
	v_pk_mul_f32 v[116:117], v[116:117], v[124:125]
	v_cvt_pk_bf16_f32 v192, v118, v119
	v_cvt_pk_bf16_f32 v193, v120, v121
	v_cvt_pk_bf16_f32 v194, v114, v115
	v_cvt_pk_bf16_f32 v195, v116, v117
	global_store_dwordx4 v[180:181], v[192:195], off offset:-4096
	s_waitcnt vmcnt(7)
	v_add_f32_e32 v140, v226, v227
	v_add_f32_e32 v141, v228, v229
	v_add_f32_e32 v140, v140, v141
	v_fmamk_f32 v140, v140, 0x3a800000, v207
	v_rsq_f32_e32 v184, v140
	s_nop 0
	v_pk_mul_f32 v[110:111], v[110:111], v[184:185] op_sel_hi:[1,0]
	v_pk_mul_f32 v[112:113], v[112:113], v[184:185] op_sel_hi:[1,0]
	v_pk_mul_f32 v[102:103], v[102:103], v[184:185] op_sel_hi:[1,0]
	v_pk_mul_f32 v[104:105], v[104:105], v[184:185] op_sel_hi:[1,0]
	v_pk_mul_f32 v[106:107], v[106:107], v[184:185] op_sel_hi:[1,0]
	v_pk_mul_f32 v[108:109], v[108:109], v[184:185] op_sel_hi:[1,0]
	v_pk_mul_f32 v[98:99], v[98:99], v[184:185] op_sel_hi:[1,0]
	v_pk_mul_f32 v[100:101], v[100:101], v[184:185] op_sel_hi:[1,0]
	v_pk_mul_f32 v[132:133], v[110:111], s[2:3]
	v_pk_mul_f32 v[134:135], v[112:113], s[2:3]
	v_pk_mul_f32 v[136:137], v[102:103], s[2:3]
	v_pk_mul_f32 v[138:139], v[104:105], s[2:3]
	v_exp_f32_e32 v132, v132
	v_exp_f32_e32 v133, v133
	v_exp_f32_e32 v134, v134
	v_exp_f32_e32 v135, v135
	v_exp_f32_e32 v136, v136
	v_exp_f32_e32 v137, v137
	v_exp_f32_e32 v138, v138
	v_exp_f32_e32 v139, v139
	v_pk_add_f32 v[132:133], v[132:133], s[100:101]
	v_pk_add_f32 v[134:135], v[134:135], s[100:101]
	v_pk_add_f32 v[136:137], v[136:137], s[100:101]
	v_pk_add_f32 v[138:139], v[138:139], s[100:101]
	v_rcp_f32_e32 v132, v132
	v_rcp_f32_e32 v133, v133
	v_rcp_f32_e32 v134, v134
	v_rcp_f32_e32 v135, v135
	v_rcp_f32_e32 v136, v136
	v_rcp_f32_e32 v137, v137
	v_rcp_f32_e32 v138, v138
	v_rcp_f32_e32 v139, v139
	v_pk_mul_f32 v[110:111], v[110:111], v[132:133]
	v_pk_mul_f32 v[112:113], v[112:113], v[134:135]
	v_pk_mul_f32 v[102:103], v[102:103], v[136:137]
	v_pk_mul_f32 v[104:105], v[104:105], v[138:139]
	v_pk_mul_f32 v[110:111], v[110:111], v[106:107]
	v_pk_mul_f32 v[112:113], v[112:113], v[108:109]
	v_pk_mul_f32 v[102:103], v[102:103], v[98:99]
	v_pk_mul_f32 v[104:105], v[104:105], v[100:101]
	v_cvt_pk_bf16_f32 v186, v110, v111
	v_cvt_pk_bf16_f32 v187, v112, v113
	v_cvt_pk_bf16_f32 v188, v102, v103
	v_cvt_pk_bf16_f32 v189, v104, v105
	global_store_dwordx4 v[180:181], v[186:189], off offset:-2048
	s_waitcnt vmcnt(7)
	v_add_f32_e32 v140, v230, v231
	v_add_f32_e32 v141, v232, v233
	v_add_f32_e32 v140, v140, v141
	v_fmamk_f32 v140, v140, 0x3a800000, v207
	v_rsq_f32_e32 v184, v140
	s_nop 0
	v_pk_mul_f32 v[92:93], v[92:93], v[184:185] op_sel_hi:[1,0]
	v_pk_mul_f32 v[94:95], v[94:95], v[184:185] op_sel_hi:[1,0]
	v_pk_mul_f32 v[84:85], v[84:85], v[184:185] op_sel_hi:[1,0]
	v_pk_mul_f32 v[86:87], v[86:87], v[184:185] op_sel_hi:[1,0]
	v_pk_mul_f32 v[88:89], v[88:89], v[184:185] op_sel_hi:[1,0]
	v_pk_mul_f32 v[90:91], v[90:91], v[184:185] op_sel_hi:[1,0]
	v_pk_mul_f32 v[80:81], v[80:81], v[184:185] op_sel_hi:[1,0]
	v_pk_mul_f32 v[82:83], v[82:83], v[184:185] op_sel_hi:[1,0]
	v_pk_mul_f32 v[132:133], v[92:93], s[2:3]
	v_pk_mul_f32 v[134:135], v[94:95], s[2:3]
	v_pk_mul_f32 v[136:137], v[84:85], s[2:3]
	v_pk_mul_f32 v[138:139], v[86:87], s[2:3]
	v_exp_f32_e32 v132, v132
	v_exp_f32_e32 v133, v133
	v_exp_f32_e32 v134, v134
	v_exp_f32_e32 v135, v135
	v_exp_f32_e32 v136, v136
	v_exp_f32_e32 v137, v137
	v_exp_f32_e32 v138, v138
	v_exp_f32_e32 v139, v139
	v_pk_add_f32 v[132:133], v[132:133], s[100:101]
	v_pk_add_f32 v[134:135], v[134:135], s[100:101]
	v_pk_add_f32 v[136:137], v[136:137], s[100:101]
	v_pk_add_f32 v[138:139], v[138:139], s[100:101]
	v_rcp_f32_e32 v132, v132
	v_rcp_f32_e32 v133, v133
	v_rcp_f32_e32 v134, v134
	v_rcp_f32_e32 v135, v135
	v_rcp_f32_e32 v136, v136
	v_rcp_f32_e32 v137, v137
	v_rcp_f32_e32 v138, v138
	v_rcp_f32_e32 v139, v139
	v_pk_mul_f32 v[92:93], v[92:93], v[132:133]
	v_pk_mul_f32 v[94:95], v[94:95], v[134:135]
	v_pk_mul_f32 v[84:85], v[84:85], v[136:137]
	v_pk_mul_f32 v[86:87], v[86:87], v[138:139]
	v_pk_mul_f32 v[92:93], v[92:93], v[88:89]
	v_pk_mul_f32 v[94:95], v[94:95], v[90:91]
	v_pk_mul_f32 v[84:85], v[84:85], v[80:81]
	v_pk_mul_f32 v[86:87], v[86:87], v[82:83]
	v_cvt_pk_bf16_f32 v192, v92, v93
	v_cvt_pk_bf16_f32 v193, v94, v95
	v_cvt_pk_bf16_f32 v194, v84, v85
	v_cvt_pk_bf16_f32 v195, v86, v87
	global_store_dwordx4 v[180:181], v[192:195], off
	s_waitcnt vmcnt(7)
	v_add_f32_e32 v140, v234, v235
	v_add_f32_e32 v141, v236, v237
	v_add_f32_e32 v140, v140, v141
	v_fmamk_f32 v140, v140, 0x3a800000, v207
	v_rsq_f32_e32 v184, v140
	s_nop 0
	v_pk_mul_f32 v[76:77], v[76:77], v[184:185] op_sel_hi:[1,0]
	v_pk_mul_f32 v[78:79], v[78:79], v[184:185] op_sel_hi:[1,0]
	v_pk_mul_f32 v[68:69], v[68:69], v[184:185] op_sel_hi:[1,0]
	v_pk_mul_f32 v[70:71], v[70:71], v[184:185] op_sel_hi:[1,0]
	v_pk_mul_f32 v[72:73], v[72:73], v[184:185] op_sel_hi:[1,0]
	v_pk_mul_f32 v[74:75], v[74:75], v[184:185] op_sel_hi:[1,0]
	v_pk_mul_f32 v[64:65], v[64:65], v[184:185] op_sel_hi:[1,0]
	v_pk_mul_f32 v[66:67], v[66:67], v[184:185] op_sel_hi:[1,0]
	v_pk_mul_f32 v[132:133], v[76:77], s[2:3]
	v_pk_mul_f32 v[134:135], v[78:79], s[2:3]
	v_pk_mul_f32 v[136:137], v[68:69], s[2:3]
	v_pk_mul_f32 v[138:139], v[70:71], s[2:3]
	v_exp_f32_e32 v132, v132
	v_exp_f32_e32 v133, v133
	v_exp_f32_e32 v134, v134
	v_exp_f32_e32 v135, v135
	v_exp_f32_e32 v136, v136
	v_exp_f32_e32 v137, v137
	v_exp_f32_e32 v138, v138
	v_exp_f32_e32 v139, v139
	v_pk_add_f32 v[132:133], v[132:133], s[100:101]
	v_pk_add_f32 v[134:135], v[134:135], s[100:101]
	v_pk_add_f32 v[136:137], v[136:137], s[100:101]
	v_pk_add_f32 v[138:139], v[138:139], s[100:101]
	v_rcp_f32_e32 v132, v132
	v_rcp_f32_e32 v133, v133
	v_rcp_f32_e32 v134, v134
	v_rcp_f32_e32 v135, v135
	v_rcp_f32_e32 v136, v136
	v_rcp_f32_e32 v137, v137
	v_rcp_f32_e32 v138, v138
	v_rcp_f32_e32 v139, v139
	v_pk_mul_f32 v[76:77], v[76:77], v[132:133]
	v_pk_mul_f32 v[78:79], v[78:79], v[134:135]
	v_pk_mul_f32 v[68:69], v[68:69], v[136:137]
	v_pk_mul_f32 v[70:71], v[70:71], v[138:139]
	v_pk_mul_f32 v[76:77], v[76:77], v[72:73]
	v_pk_mul_f32 v[78:79], v[78:79], v[74:75]
	v_pk_mul_f32 v[68:69], v[68:69], v[64:65]
	v_pk_mul_f32 v[70:71], v[70:71], v[66:67]
	v_cvt_pk_bf16_f32 v186, v76, v77
	v_cvt_pk_bf16_f32 v187, v78, v79
	v_cvt_pk_bf16_f32 v188, v68, v69
	v_cvt_pk_bf16_f32 v189, v70, v71
	global_store_dwordx4 v[180:181], v[186:189], off offset:2048
	s_waitcnt vmcnt(7)
	v_add_f32_e32 v140, v238, v239
	v_add_f32_e32 v141, v240, v241
	v_add_f32_e32 v140, v140, v141
	v_fmamk_f32 v140, v140, 0x3a800000, v207
	v_rsq_f32_e32 v184, v140
	s_nop 0
	v_pk_mul_f32 v[60:61], v[60:61], v[184:185] op_sel_hi:[1,0]
	v_pk_mul_f32 v[62:63], v[62:63], v[184:185] op_sel_hi:[1,0]
	v_pk_mul_f32 v[52:53], v[52:53], v[184:185] op_sel_hi:[1,0]
	v_pk_mul_f32 v[54:55], v[54:55], v[184:185] op_sel_hi:[1,0]
	v_pk_mul_f32 v[56:57], v[56:57], v[184:185] op_sel_hi:[1,0]
	v_pk_mul_f32 v[58:59], v[58:59], v[184:185] op_sel_hi:[1,0]
	v_pk_mul_f32 v[48:49], v[48:49], v[184:185] op_sel_hi:[1,0]
	v_pk_mul_f32 v[50:51], v[50:51], v[184:185] op_sel_hi:[1,0]
	v_pk_mul_f32 v[132:133], v[60:61], s[2:3]
	v_pk_mul_f32 v[134:135], v[62:63], s[2:3]
	v_pk_mul_f32 v[136:137], v[52:53], s[2:3]
	v_pk_mul_f32 v[138:139], v[54:55], s[2:3]
	v_exp_f32_e32 v132, v132
	v_exp_f32_e32 v133, v133
	v_exp_f32_e32 v134, v134
	v_exp_f32_e32 v135, v135
	v_exp_f32_e32 v136, v136
	v_exp_f32_e32 v137, v137
	v_exp_f32_e32 v138, v138
	v_exp_f32_e32 v139, v139
	v_pk_add_f32 v[132:133], v[132:133], s[100:101]
	v_pk_add_f32 v[134:135], v[134:135], s[100:101]
	v_pk_add_f32 v[136:137], v[136:137], s[100:101]
	v_pk_add_f32 v[138:139], v[138:139], s[100:101]
	v_rcp_f32_e32 v132, v132
	v_rcp_f32_e32 v133, v133
	v_rcp_f32_e32 v134, v134
	v_rcp_f32_e32 v135, v135
	v_rcp_f32_e32 v136, v136
	v_rcp_f32_e32 v137, v137
	v_rcp_f32_e32 v138, v138
	v_rcp_f32_e32 v139, v139
	v_pk_mul_f32 v[60:61], v[60:61], v[132:133]
	v_pk_mul_f32 v[62:63], v[62:63], v[134:135]
	v_pk_mul_f32 v[52:53], v[52:53], v[136:137]
	v_pk_mul_f32 v[54:55], v[54:55], v[138:139]
	v_pk_mul_f32 v[60:61], v[60:61], v[56:57]
	v_pk_mul_f32 v[62:63], v[62:63], v[58:59]
	v_pk_mul_f32 v[52:53], v[52:53], v[48:49]
	v_pk_mul_f32 v[54:55], v[54:55], v[50:51]
	v_cvt_pk_bf16_f32 v192, v60, v61
	v_cvt_pk_bf16_f32 v193, v62, v63
	v_cvt_pk_bf16_f32 v194, v52, v53
	v_cvt_pk_bf16_f32 v195, v54, v55
	global_store_dwordx4 v[182:183], v[192:195], off offset:-4096
	s_waitcnt vmcnt(7)
	v_add_f32_e32 v140, v242, v243
	v_add_f32_e32 v141, v244, v245
	v_add_f32_e32 v140, v140, v141
	v_fmamk_f32 v140, v140, 0x3a800000, v207
	v_rsq_f32_e32 v184, v140
	s_nop 0
	v_pk_mul_f32 v[44:45], v[44:45], v[184:185] op_sel_hi:[1,0]
	v_pk_mul_f32 v[46:47], v[46:47], v[184:185] op_sel_hi:[1,0]
	v_pk_mul_f32 v[36:37], v[36:37], v[184:185] op_sel_hi:[1,0]
	v_pk_mul_f32 v[38:39], v[38:39], v[184:185] op_sel_hi:[1,0]
	v_pk_mul_f32 v[40:41], v[40:41], v[184:185] op_sel_hi:[1,0]
	v_pk_mul_f32 v[42:43], v[42:43], v[184:185] op_sel_hi:[1,0]
	v_pk_mul_f32 v[32:33], v[32:33], v[184:185] op_sel_hi:[1,0]
	v_pk_mul_f32 v[34:35], v[34:35], v[184:185] op_sel_hi:[1,0]
	v_pk_mul_f32 v[132:133], v[44:45], s[2:3]
	v_pk_mul_f32 v[134:135], v[46:47], s[2:3]
	v_pk_mul_f32 v[136:137], v[36:37], s[2:3]
	v_pk_mul_f32 v[138:139], v[38:39], s[2:3]
	v_exp_f32_e32 v132, v132
	v_exp_f32_e32 v133, v133
	v_exp_f32_e32 v134, v134
	v_exp_f32_e32 v135, v135
	v_exp_f32_e32 v136, v136
	v_exp_f32_e32 v137, v137
	v_exp_f32_e32 v138, v138
	v_exp_f32_e32 v139, v139
	v_pk_add_f32 v[132:133], v[132:133], s[100:101]
	v_pk_add_f32 v[134:135], v[134:135], s[100:101]
	v_pk_add_f32 v[136:137], v[136:137], s[100:101]
	v_pk_add_f32 v[138:139], v[138:139], s[100:101]
	v_rcp_f32_e32 v132, v132
	v_rcp_f32_e32 v133, v133
	v_rcp_f32_e32 v134, v134
	v_rcp_f32_e32 v135, v135
	v_rcp_f32_e32 v136, v136
	v_rcp_f32_e32 v137, v137
	v_rcp_f32_e32 v138, v138
	v_rcp_f32_e32 v139, v139
	v_pk_mul_f32 v[44:45], v[44:45], v[132:133]
	v_pk_mul_f32 v[46:47], v[46:47], v[134:135]
	v_pk_mul_f32 v[36:37], v[36:37], v[136:137]
	v_pk_mul_f32 v[38:39], v[38:39], v[138:139]
	v_pk_mul_f32 v[44:45], v[44:45], v[40:41]
	v_pk_mul_f32 v[46:47], v[46:47], v[42:43]
	v_pk_mul_f32 v[36:37], v[36:37], v[32:33]
	v_pk_mul_f32 v[38:39], v[38:39], v[34:35]
	v_cvt_pk_bf16_f32 v186, v44, v45
	v_cvt_pk_bf16_f32 v187, v46, v47
	v_cvt_pk_bf16_f32 v188, v36, v37
	v_cvt_pk_bf16_f32 v189, v38, v39
	global_store_dwordx4 v[182:183], v[186:189], off offset:-2048
	s_waitcnt vmcnt(7)
	v_add_f32_e32 v140, v198, v199
	v_add_f32_e32 v141, v200, v201
	v_add_f32_e32 v140, v140, v141
	v_fmamk_f32 v140, v140, 0x3a800000, v207
	v_rsq_f32_e32 v184, v140
	s_nop 0
	v_pk_mul_f32 v[28:29], v[28:29], v[184:185] op_sel_hi:[1,0]
	v_pk_mul_f32 v[30:31], v[30:31], v[184:185] op_sel_hi:[1,0]
	v_pk_mul_f32 v[20:21], v[20:21], v[184:185] op_sel_hi:[1,0]
	v_pk_mul_f32 v[22:23], v[22:23], v[184:185] op_sel_hi:[1,0]
	v_pk_mul_f32 v[24:25], v[24:25], v[184:185] op_sel_hi:[1,0]
	v_pk_mul_f32 v[26:27], v[26:27], v[184:185] op_sel_hi:[1,0]
	v_pk_mul_f32 v[16:17], v[16:17], v[184:185] op_sel_hi:[1,0]
	v_pk_mul_f32 v[18:19], v[18:19], v[184:185] op_sel_hi:[1,0]
	v_pk_mul_f32 v[132:133], v[28:29], s[2:3]
	v_pk_mul_f32 v[134:135], v[30:31], s[2:3]
	v_pk_mul_f32 v[136:137], v[20:21], s[2:3]
	v_pk_mul_f32 v[138:139], v[22:23], s[2:3]
	v_exp_f32_e32 v132, v132
	v_exp_f32_e32 v133, v133
	v_exp_f32_e32 v134, v134
	v_exp_f32_e32 v135, v135
	v_exp_f32_e32 v136, v136
	v_exp_f32_e32 v137, v137
	v_exp_f32_e32 v138, v138
	v_exp_f32_e32 v139, v139
	v_pk_add_f32 v[132:133], v[132:133], s[100:101]
	v_pk_add_f32 v[134:135], v[134:135], s[100:101]
	v_pk_add_f32 v[136:137], v[136:137], s[100:101]
	v_pk_add_f32 v[138:139], v[138:139], s[100:101]
	v_rcp_f32_e32 v132, v132
	v_rcp_f32_e32 v133, v133
	v_rcp_f32_e32 v134, v134
	v_rcp_f32_e32 v135, v135
	v_rcp_f32_e32 v136, v136
	v_rcp_f32_e32 v137, v137
	v_rcp_f32_e32 v138, v138
	v_rcp_f32_e32 v139, v139
	v_pk_mul_f32 v[28:29], v[28:29], v[132:133]
	v_pk_mul_f32 v[30:31], v[30:31], v[134:135]
	v_pk_mul_f32 v[20:21], v[20:21], v[136:137]
	v_pk_mul_f32 v[22:23], v[22:23], v[138:139]
	v_pk_mul_f32 v[28:29], v[28:29], v[24:25]
	v_pk_mul_f32 v[30:31], v[30:31], v[26:27]
	v_pk_mul_f32 v[20:21], v[20:21], v[16:17]
	v_pk_mul_f32 v[22:23], v[22:23], v[18:19]
	v_cvt_pk_bf16_f32 v192, v28, v29
	v_cvt_pk_bf16_f32 v193, v30, v31
	v_cvt_pk_bf16_f32 v194, v20, v21
	v_cvt_pk_bf16_f32 v195, v22, v23
	global_store_dwordx4 v[182:183], v[192:195], off
	s_waitcnt vmcnt(7)
	v_add_f32_e32 v140, v202, v203
	v_add_f32_e32 v141, v204, v205
	v_add_f32_e32 v140, v140, v141
	v_fmamk_f32 v140, v140, 0x3a800000, v207
	v_rsq_f32_e32 v184, v140
	s_nop 0
	v_pk_mul_f32 v[12:13], v[12:13], v[184:185] op_sel_hi:[1,0]
	v_pk_mul_f32 v[14:15], v[14:15], v[184:185] op_sel_hi:[1,0]
	v_pk_mul_f32 v[4:5], v[4:5], v[184:185] op_sel_hi:[1,0]
	v_pk_mul_f32 v[6:7], v[6:7], v[184:185] op_sel_hi:[1,0]
	v_pk_mul_f32 v[8:9], v[8:9], v[184:185] op_sel_hi:[1,0]
	v_pk_mul_f32 v[10:11], v[10:11], v[184:185] op_sel_hi:[1,0]
	v_pk_mul_f32 v[0:1], v[0:1], v[184:185] op_sel_hi:[1,0]
	v_pk_mul_f32 v[2:3], v[2:3], v[184:185] op_sel_hi:[1,0]
	v_pk_mul_f32 v[132:133], v[12:13], s[2:3]
	v_pk_mul_f32 v[134:135], v[14:15], s[2:3]
	v_pk_mul_f32 v[136:137], v[4:5], s[2:3]
	v_pk_mul_f32 v[138:139], v[6:7], s[2:3]
	v_exp_f32_e32 v132, v132
	v_exp_f32_e32 v133, v133
	v_exp_f32_e32 v134, v134
	v_exp_f32_e32 v135, v135
	v_exp_f32_e32 v136, v136
	v_exp_f32_e32 v137, v137
	v_exp_f32_e32 v138, v138
	v_exp_f32_e32 v139, v139
	v_pk_add_f32 v[132:133], v[132:133], s[100:101]
	v_pk_add_f32 v[134:135], v[134:135], s[100:101]
	v_pk_add_f32 v[136:137], v[136:137], s[100:101]
	v_pk_add_f32 v[138:139], v[138:139], s[100:101]
	v_rcp_f32_e32 v132, v132
	v_rcp_f32_e32 v133, v133
	v_rcp_f32_e32 v134, v134
	v_rcp_f32_e32 v135, v135
	v_rcp_f32_e32 v136, v136
	v_rcp_f32_e32 v137, v137
	v_rcp_f32_e32 v138, v138
	v_rcp_f32_e32 v139, v139
	v_pk_mul_f32 v[12:13], v[12:13], v[132:133]
	v_pk_mul_f32 v[14:15], v[14:15], v[134:135]
	v_pk_mul_f32 v[4:5], v[4:5], v[136:137]
	v_pk_mul_f32 v[6:7], v[6:7], v[138:139]
	v_pk_mul_f32 v[12:13], v[12:13], v[8:9]
	v_pk_mul_f32 v[14:15], v[14:15], v[10:11]
	v_pk_mul_f32 v[4:5], v[4:5], v[0:1]
	v_pk_mul_f32 v[6:7], v[6:7], v[2:3]
	v_cvt_pk_bf16_f32 v186, v12, v13
	v_cvt_pk_bf16_f32 v187, v14, v15
	v_cvt_pk_bf16_f32 v188, v4, v5
	v_cvt_pk_bf16_f32 v189, v6, v7
	global_store_dwordx4 v[182:183], v[186:189], off offset:2048
	s_mov_b32 s101, 1
	s_mov_b64 s[0:1], -1
	s_andn2_b64 vcc, exec, s[4:5]
	s_cbranch_vccnz .LBB0_1127
	s_andn2_b64 vcc, exec, s[6:7]
	s_cbranch_vccnz .LBB0_1126
	s_barrier
	s_branch .LBB0_1126
